# MFMA segment trim: the s_setprio 0/1 flip pair in the middle of each 32-MFMA block removed in all six GEMM K-loops (block-start raise and block-end lower kept), on top of v9
# speedup vs baseline: 1.0101x; 1.0027x over previous
; #define PG8_STAGE(bufoff, gbase, voff) do { _Pragma("unroll") for (int _i = 0; _i < 2; ++_i) \
;         __builtin_amdgcn_global_load_lds((const unsigned*)((const char*)(gbase) + (voff)[_i]), (PG8_LAS unsigned*)(lds + (bufoff) + ldsw + _i * 8192), 16, 0, 0); } while (0)
; #define PG8_LDA(dst, b, h) do { _Pragma("unroll") for (int m = 0; m < 4; ++m) _Pragma("unroll") for (int k = 0; k < 2; ++k) dst[m][k] = *(const PG8_LAS bf16x8*)(lds + PG8_SA(b, h) + aoff + m * 2048 + k * 1024); } while (0)
; #define PG8_LDB(dst, b, h) do { _Pragma("unroll") for (int n = 0; n < 2; ++n) _Pragma("unroll") for (int k = 0; k < 2; ++k) dst[n][k] = *(const PG8_LAS bf16x8*)(lds + PG8_SB(b, h) + boff + n * 2048 + k * 1024); } while (0)
; #define PG8_MMA(ai, bj, At, Bt) do { __builtin_amdgcn_s_setprio(1); _Pragma("unroll") for (int m = 0; m < 4; ++m) _Pragma("unroll") for (int n = 0; n < 2; ++n) _Pragma("unroll") for (int k = 0; k < 2; ++k) \
;         acc[ai][bj][m][n] = __builtin_amdgcn_mfma_f32_16x16x32_bf16(Bt[n][k], At[m][k], acc[ai][bj][m][n], 0, 0, 0); __builtin_amdgcn_s_setprio(0); } while (0)
; #define PG8_WAIT_V(n) asm volatile("s_waitcnt vmcnt(" #n ")" ::: "memory")
; #define PG8_WAIT_L(n) asm volatile("s_waitcnt lgkmcnt(" #n ")" ::: "memory")
; template <class Epi, class Sched, bool ALIGN_EPI = false, bool SP2 = false>
; __device__ __forceinline__ void gemm_phase(PG8_LAS unsigned char* lds, const Gemm g, const Sched& S, const Epi& E) {
;     ...
;             const bool last = (t == nt - 2);
;             const char* a1 = cA + (size_t)(t + 1) * kstep;
;             const char* a2 = last ? nA : cA + (size_t)(t + 2) * kstep; const char* b2 = last ? nB : cB + (size_t)(t + 2) * kstep;
;             const char* a3 = a2 + kstep; const char* b3 = b2 + kstep;
;             if (last && has_next) S.a_ready(nxt);
;             if constexpr (SP2) {
;             PG8_LDB(B0, 0, 0); PG8_LDB(B1, 0, 1); PG8_SCHED; PG8_LDA(At, 0, 0); PG8_STAGE(PG8_SA(1, 1), a1 + hstep, voffA);
;             PG8_WAIT_V(8); PG8_WAIT_L(0); PG8_BAR; PG8_MMA(0, 0, At, B0); PG8_MMA(0, 1, At, B1); PG8_BAR; PG8_SCHED;
;             PG8_LDA(At, 0, 1); PG8_STAGE(PG8_SB(0, 0), b2, voffB); PG8_STAGE(PG8_SB(0, 1), b2 + hstep, voffB); PG8_STAGE(PG8_SA(0, 0), a2, voffA);
;             PG8_WAIT_V(8); PG8_WAIT_L(0); PG8_BAR; PG8_MMA(1, 0, At, B0); PG8_MMA(1, 1, At, B1); PG8_BAR; PG8_SCHED;
.LBB0_147:
	s_add_u32 s12, s56, 0xfff80080
	s_addc_u32 s13, s57, -1
	s_add_i32 s85, 0, 0x10000
	s_cmp_eq_u32 s84, 28
	s_cselect_b32 s61, s18, s13
	s_cselect_b32 s60, s19, s12
	v_add_u32_e32 v142, s85, v145
	s_cselect_b32 s59, s43, s73
	s_cselect_b32 s58, s47, s72
	s_add_i32 s92, 0, 0x14000
	ds_read_b128 v[148:151], v142
	ds_read_b128 v[152:155], v142 offset:1024
	ds_read_b128 v[156:159], v142 offset:2048
	ds_read_b128 v[160:163], v142 offset:3072
	v_add_u32_e32 v142, s92, v145
	ds_read_b128 v[164:167], v142
	ds_read_b128 v[168:171], v142 offset:1024
	ds_read_b128 v[172:175], v142 offset:2048
	ds_read_b128 v[176:179], v142 offset:3072
	v_lshl_add_u64 v[142:143], s[56:57], 0, v[140:141]
	s_add_i32 m0, s55, 0xc000
	ds_read_b128 v[180:183], v147
	ds_read_b128 v[184:187], v147 offset:1024
	ds_read_b128 v[188:191], v147 offset:2048
	ds_read_b128 v[202:205], v147 offset:3072
	ds_read_b128 v[206:209], v147 offset:4096
	ds_read_b128 v[210:213], v147 offset:5120
	ds_read_b128 v[214:217], v147 offset:6144
	ds_read_b128 v[218:221], v147 offset:7168
	global_load_lds_dwordx4 v[142:143], off
	v_lshl_add_u64 v[142:143], s[56:57], 0, v[138:139]
	s_add_i32 m0, s55, 0xe000
	s_nop 0
	global_load_lds_dwordx4 v[142:143], off
	s_waitcnt vmcnt(8)
	s_waitcnt lgkmcnt(0)
	s_barrier
	s_setprio 1
	s_waitcnt lgkmcnt(0)
	v_mfma_f32_16x16x32_bf16 v[126:129], v[148:151], v[180:183], v[126:129]
	v_mfma_f32_16x16x32_bf16 v[122:125], v[156:159], v[180:183], v[122:125]
	v_mfma_f32_16x16x32_bf16 v[118:121], v[148:151], v[188:191], v[118:121]
	v_mfma_f32_16x16x32_bf16 v[110:113], v[156:159], v[188:191], v[110:113]
	v_mfma_f32_16x16x32_bf16 v[102:105], v[148:151], v[206:209], v[102:105]
	v_mfma_f32_16x16x32_bf16 v[92:95], v[156:159], v[206:209], v[92:95]
	v_mfma_f32_16x16x32_bf16 v[84:87], v[148:151], v[214:217], v[84:87]
	v_mfma_f32_16x16x32_bf16 v[76:79], v[156:159], v[214:217], v[76:79]
	v_mfma_f32_16x16x32_bf16 v[126:129], v[152:155], v[184:187], v[126:129]
	v_mfma_f32_16x16x32_bf16 v[122:125], v[160:163], v[184:187], v[122:125]
	v_mfma_f32_16x16x32_bf16 v[118:121], v[152:155], v[202:205], v[118:121]
	v_mfma_f32_16x16x32_bf16 v[110:113], v[160:163], v[202:205], v[110:113]
	v_mfma_f32_16x16x32_bf16 v[102:105], v[152:155], v[210:213], v[102:105]
	v_mfma_f32_16x16x32_bf16 v[92:95], v[160:163], v[210:213], v[92:95]
	v_mfma_f32_16x16x32_bf16 v[84:87], v[152:155], v[218:221], v[84:87]
	v_mfma_f32_16x16x32_bf16 v[76:79], v[160:163], v[218:221], v[76:79]
	v_mfma_f32_16x16x32_bf16 v[114:117], v[164:167], v[180:183], v[114:117]
	v_mfma_f32_16x16x32_bf16 v[106:109], v[172:175], v[180:183], v[106:109]
	v_mfma_f32_16x16x32_bf16 v[98:101], v[164:167], v[188:191], v[98:101]
	v_mfma_f32_16x16x32_bf16 v[88:91], v[172:175], v[188:191], v[88:91]
	v_mfma_f32_16x16x32_bf16 v[80:83], v[164:167], v[206:209], v[80:83]
	v_mfma_f32_16x16x32_bf16 v[72:75], v[172:175], v[206:209], v[72:75]
	v_mfma_f32_16x16x32_bf16 v[68:71], v[164:167], v[214:217], v[68:71]
	v_mfma_f32_16x16x32_bf16 v[64:67], v[172:175], v[214:217], v[64:67]
	v_mfma_f32_16x16x32_bf16 v[114:117], v[168:171], v[184:187], v[114:117]
	v_mfma_f32_16x16x32_bf16 v[106:109], v[176:179], v[184:187], v[106:109]
	v_mfma_f32_16x16x32_bf16 v[98:101], v[168:171], v[202:205], v[98:101]
	v_mfma_f32_16x16x32_bf16 v[88:91], v[176:179], v[202:205], v[88:91]
	v_mfma_f32_16x16x32_bf16 v[80:83], v[168:171], v[210:213], v[80:83]
	v_mfma_f32_16x16x32_bf16 v[72:75], v[176:179], v[210:213], v[72:75]
	v_mfma_f32_16x16x32_bf16 v[68:71], v[168:171], v[218:221], v[68:71]
	v_mfma_f32_16x16x32_bf16 v[64:67], v[176:179], v[218:221], v[64:67]
	s_setprio 0
	s_barrier
	s_add_i32 s12, s85, s63
	v_lshl_add_u64 v[142:143], s[58:59], 0, v[132:133]
	s_mov_b32 m0, s12
	ds_read_b128 v[180:183], v147 offset:16384
	ds_read_b128 v[184:187], v147 offset:17408
	ds_read_b128 v[188:191], v147 offset:18432
	ds_read_b128 v[202:205], v147 offset:19456
	ds_read_b128 v[206:209], v147 offset:20480
	ds_read_b128 v[210:213], v147 offset:21504
	ds_read_b128 v[214:217], v147 offset:22528
	ds_read_b128 v[218:221], v147 offset:23552
	global_load_lds_dwordx4 v[142:143], off
	s_add_i32 m0, s12, 0x2000
	s_add_u32 s12, s58, 0x80000
	v_lshl_add_u64 v[192:193], s[58:59], 0, v[136:137]
	s_addc_u32 s13, s59, 0
	s_add_i32 s85, s92, s63
	global_load_lds_dwordx4 v[192:193], off
	v_lshl_add_u64 v[222:223], s[12:13], 0, v[132:133]
	s_mov_b32 m0, s85
	v_lshl_add_u64 v[224:225], s[60:61], 0, v[134:135]
	global_load_lds_dwordx4 v[222:223], off
	v_lshl_add_u64 v[222:223], s[12:13], 0, v[136:137]
	s_add_i32 m0, s85, 0x2000
	s_nop 0
	global_load_lds_dwordx4 v[222:223], off
	v_lshl_add_u64 v[222:223], s[60:61], 0, v[130:131]
	s_mov_b32 m0, s55
	s_nop 0
	global_load_lds_dwordx4 v[222:223], off
	s_mov_b32 m0, s64
	s_nop 0
	global_load_lds_dwordx4 v[224:225], off
	s_waitcnt vmcnt(8)
	s_waitcnt lgkmcnt(0)
	s_barrier
; #define PG8_STAGE(bufoff, gbase, voff) do { _Pragma("unroll") for (int _i = 0; _i < 2; ++_i) \
;         __builtin_amdgcn_global_load_lds((const unsigned*)((const char*)(gbase) + (voff)[_i]), (PG8_LAS unsigned*)(lds + (bufoff) + ldsw + _i * 8192), 16, 0, 0); } while (0)
; #define PG8_LDA(dst, b, h) do { _Pragma("unroll") for (int m = 0; m < 4; ++m) _Pragma("unroll") for (int k = 0; k < 2; ++k) dst[m][k] = *(const PG8_LAS bf16x8*)(lds + PG8_SA(b, h) + aoff + m * 2048 + k * 1024); } while (0)
; #define PG8_LDB(dst, b, h) do { _Pragma("unroll") for (int n = 0; n < 2; ++n) _Pragma("unroll") for (int k = 0; k < 2; ++k) dst[n][k] = *(const PG8_LAS bf16x8*)(lds + PG8_SB(b, h) + boff + n * 2048 + k * 1024); } while (0)
; #define PG8_MMA(ai, bj, At, Bt) do { __builtin_amdgcn_s_setprio(1); _Pragma("unroll") for (int m = 0; m < 4; ++m) _Pragma("unroll") for (int n = 0; n < 2; ++n) _Pragma("unroll") for (int k = 0; k < 2; ++k) \
;         acc[ai][bj][m][n] = __builtin_amdgcn_mfma_f32_16x16x32_bf16(Bt[n][k], At[m][k], acc[ai][bj][m][n], 0, 0, 0); __builtin_amdgcn_s_setprio(0); } while (0)
; #define PG8_WAIT_V(n) asm volatile("s_waitcnt vmcnt(" #n ")" ::: "memory")
; #define PG8_WAIT_L(n) asm volatile("s_waitcnt lgkmcnt(" #n ")" ::: "memory")
; #define PG8_BAR __builtin_amdgcn_s_barrier()
; #define PG8_SCHED __builtin_amdgcn_sched_barrier(0)
; template <class Epi, class Sched, bool ALIGN_EPI = false, bool SP2 = false>
; __device__ __forceinline__ void gemm_phase(PG8_LAS unsigned char* lds, const Gemm g, const Sched& S, const Epi& E) {
;     ...
;             PG8_WAIT_V(8); PG8_WAIT_L(0); PG8_BAR; PG8_MMA(1, 0, At, B0); PG8_MMA(1, 1, At, B1); PG8_BAR; PG8_SCHED;
;             PG8_LDB(B0, 1, 0); PG8_LDB(B1, 1, 1); PG8_SCHED; PG8_LDA(At, 1, 0); PG8_STAGE(PG8_SA(0, 1), a2 + hstep, voffA);
;             PG8_WAIT_V(8); PG8_WAIT_L(0); PG8_BAR; PG8_MMA(0, 0, At, B0); PG8_MMA(0, 1, At, B1); PG8_BAR; PG8_SCHED;
	s_setprio 1
	s_waitcnt lgkmcnt(0)
	v_mfma_f32_16x16x32_bf16 v[60:63], v[148:151], v[180:183], v[60:63]
	v_mfma_f32_16x16x32_bf16 v[56:59], v[156:159], v[180:183], v[56:59]
	v_mfma_f32_16x16x32_bf16 v[52:55], v[148:151], v[188:191], v[52:55]
	v_mfma_f32_16x16x32_bf16 v[44:47], v[156:159], v[188:191], v[44:47]
	v_mfma_f32_16x16x32_bf16 v[36:39], v[148:151], v[206:209], v[36:39]
	v_mfma_f32_16x16x32_bf16 v[28:31], v[156:159], v[206:209], v[28:31]
	v_mfma_f32_16x16x32_bf16 v[20:23], v[148:151], v[214:217], v[20:23]
	v_mfma_f32_16x16x32_bf16 v[12:15], v[156:159], v[214:217], v[12:15]
	v_mfma_f32_16x16x32_bf16 v[60:63], v[152:155], v[184:187], v[60:63]
	v_mfma_f32_16x16x32_bf16 v[56:59], v[160:163], v[184:187], v[56:59]
	v_mfma_f32_16x16x32_bf16 v[52:55], v[152:155], v[202:205], v[52:55]
	v_mfma_f32_16x16x32_bf16 v[44:47], v[160:163], v[202:205], v[44:47]
	v_mfma_f32_16x16x32_bf16 v[36:39], v[152:155], v[210:213], v[36:39]
	v_mfma_f32_16x16x32_bf16 v[28:31], v[160:163], v[210:213], v[28:31]
	v_mfma_f32_16x16x32_bf16 v[20:23], v[152:155], v[218:221], v[20:23]
	v_mfma_f32_16x16x32_bf16 v[12:15], v[160:163], v[218:221], v[12:15]
	v_mfma_f32_16x16x32_bf16 v[48:51], v[164:167], v[180:183], v[48:51]
	v_mfma_f32_16x16x32_bf16 v[40:43], v[172:175], v[180:183], v[40:43]
	v_mfma_f32_16x16x32_bf16 v[32:35], v[164:167], v[188:191], v[32:35]
	v_mfma_f32_16x16x32_bf16 v[24:27], v[172:175], v[188:191], v[24:27]
	v_mfma_f32_16x16x32_bf16 v[16:19], v[164:167], v[206:209], v[16:19]
	v_mfma_f32_16x16x32_bf16 v[8:11], v[172:175], v[206:209], v[8:11]
	v_mfma_f32_16x16x32_bf16 v[4:7], v[164:167], v[214:217], v[4:7]
	v_mfma_f32_16x16x32_bf16 v[0:3], v[172:175], v[214:217], v[0:3]
	v_mfma_f32_16x16x32_bf16 v[48:51], v[168:171], v[184:187], v[48:51]
	v_mfma_f32_16x16x32_bf16 v[40:43], v[176:179], v[184:187], v[40:43]
	v_mfma_f32_16x16x32_bf16 v[32:35], v[168:171], v[202:205], v[32:35]
	v_mfma_f32_16x16x32_bf16 v[24:27], v[176:179], v[202:205], v[24:27]
	v_mfma_f32_16x16x32_bf16 v[16:19], v[168:171], v[210:213], v[16:19]
	v_mfma_f32_16x16x32_bf16 v[8:11], v[176:179], v[210:213], v[8:11]
	v_mfma_f32_16x16x32_bf16 v[4:7], v[168:171], v[218:221], v[4:7]
	v_mfma_f32_16x16x32_bf16 v[0:3], v[176:179], v[218:221], v[0:3]
	s_setprio 0
	s_barrier
	s_add_i32 s85, 0, 0x18000
	s_add_i32 s92, 0, 0x1c000
	v_add_u32_e32 v160, s85, v145
	v_add_u32_e32 v176, s92, v145
	ds_read_b128 v[148:151], v160
	ds_read_b128 v[152:155], v160 offset:1024
	ds_read_b128 v[156:159], v160 offset:2048
	ds_read_b128 v[160:163], v160 offset:3072
	ds_read_b128 v[164:167], v176
	ds_read_b128 v[168:171], v176 offset:1024
	ds_read_b128 v[172:175], v176 offset:2048
	ds_read_b128 v[176:179], v176 offset:3072
	s_add_u32 s12, s60, 0x80000
	s_addc_u32 s13, s61, 0
	s_mov_b32 m0, s65
	v_lshl_add_u64 v[226:227], s[12:13], 0, v[130:131]
	ds_read_b128 v[180:183], v147 offset:32768
	ds_read_b128 v[184:187], v147 offset:33792
	ds_read_b128 v[188:191], v147 offset:34816
	ds_read_b128 v[202:205], v147 offset:35840
	ds_read_b128 v[206:209], v147 offset:36864
	ds_read_b128 v[210:213], v147 offset:37888
	ds_read_b128 v[214:217], v147 offset:38912
	ds_read_b128 v[218:221], v147 offset:39936
	global_load_lds_dwordx4 v[226:227], off
	v_lshl_add_u64 v[226:227], s[12:13], 0, v[134:135]
	s_mov_b32 m0, s67
	s_nop 0
	global_load_lds_dwordx4 v[226:227], off
	s_waitcnt vmcnt(8)
	s_waitcnt lgkmcnt(0)
	s_barrier
	s_setprio 1
	s_waitcnt lgkmcnt(0)
	v_mfma_f32_16x16x32_bf16 v[126:129], v[148:151], v[180:183], v[126:129]
	v_mfma_f32_16x16x32_bf16 v[122:125], v[156:159], v[180:183], v[122:125]
	v_mfma_f32_16x16x32_bf16 v[118:121], v[148:151], v[188:191], v[118:121]
	v_mfma_f32_16x16x32_bf16 v[110:113], v[156:159], v[188:191], v[110:113]
	v_mfma_f32_16x16x32_bf16 v[102:105], v[148:151], v[206:209], v[102:105]
	v_mfma_f32_16x16x32_bf16 v[92:95], v[156:159], v[206:209], v[92:95]
	v_mfma_f32_16x16x32_bf16 v[84:87], v[148:151], v[214:217], v[84:87]
	v_mfma_f32_16x16x32_bf16 v[76:79], v[156:159], v[214:217], v[76:79]
	v_mfma_f32_16x16x32_bf16 v[126:129], v[152:155], v[184:187], v[126:129]
	v_mfma_f32_16x16x32_bf16 v[122:125], v[160:163], v[184:187], v[122:125]
	v_mfma_f32_16x16x32_bf16 v[118:121], v[152:155], v[202:205], v[118:121]
	v_mfma_f32_16x16x32_bf16 v[110:113], v[160:163], v[202:205], v[110:113]
	v_mfma_f32_16x16x32_bf16 v[102:105], v[152:155], v[210:213], v[102:105]
	v_mfma_f32_16x16x32_bf16 v[92:95], v[160:163], v[210:213], v[92:95]
	v_mfma_f32_16x16x32_bf16 v[84:87], v[152:155], v[218:221], v[84:87]
	v_mfma_f32_16x16x32_bf16 v[76:79], v[160:163], v[218:221], v[76:79]
	v_mfma_f32_16x16x32_bf16 v[114:117], v[164:167], v[180:183], v[114:117]
	v_mfma_f32_16x16x32_bf16 v[106:109], v[172:175], v[180:183], v[106:109]
	v_mfma_f32_16x16x32_bf16 v[98:101], v[164:167], v[188:191], v[98:101]
	v_mfma_f32_16x16x32_bf16 v[88:91], v[172:175], v[188:191], v[88:91]
	v_mfma_f32_16x16x32_bf16 v[80:83], v[164:167], v[206:209], v[80:83]
	v_mfma_f32_16x16x32_bf16 v[72:75], v[172:175], v[206:209], v[72:75]
	v_mfma_f32_16x16x32_bf16 v[68:71], v[164:167], v[214:217], v[68:71]
	v_mfma_f32_16x16x32_bf16 v[64:67], v[172:175], v[214:217], v[64:67]
	v_mfma_f32_16x16x32_bf16 v[114:117], v[168:171], v[184:187], v[114:117]
	v_mfma_f32_16x16x32_bf16 v[106:109], v[176:179], v[184:187], v[106:109]
	v_mfma_f32_16x16x32_bf16 v[98:101], v[168:171], v[202:205], v[98:101]
	v_mfma_f32_16x16x32_bf16 v[88:91], v[176:179], v[202:205], v[88:91]
	v_mfma_f32_16x16x32_bf16 v[80:83], v[168:171], v[210:213], v[80:83]
	v_mfma_f32_16x16x32_bf16 v[72:75], v[176:179], v[210:213], v[72:75]
	v_mfma_f32_16x16x32_bf16 v[68:71], v[168:171], v[218:221], v[68:71]
	v_mfma_f32_16x16x32_bf16 v[64:67], v[176:179], v[218:221], v[64:67]
	s_setprio 0
	s_barrier
; #define PG8_STAGE(bufoff, gbase, voff) do { _Pragma("unroll") for (int _i = 0; _i < 2; ++_i) \
;         __builtin_amdgcn_global_load_lds((const unsigned*)((const char*)(gbase) + (voff)[_i]), (PG8_LAS unsigned*)(lds + (bufoff) + ldsw + _i * 8192), 16, 0, 0); } while (0)
; #define PG8_LDA(dst, b, h) do { _Pragma("unroll") for (int m = 0; m < 4; ++m) _Pragma("unroll") for (int k = 0; k < 2; ++k) dst[m][k] = *(const PG8_LAS bf16x8*)(lds + PG8_SA(b, h) + aoff + m * 2048 + k * 1024); } while (0)
; #define PG8_MMA(ai, bj, At, Bt) do { __builtin_amdgcn_s_setprio(1); _Pragma("unroll") for (int m = 0; m < 4; ++m) _Pragma("unroll") for (int n = 0; n < 2; ++n) _Pragma("unroll") for (int k = 0; k < 2; ++k) \
;         acc[ai][bj][m][n] = __builtin_amdgcn_mfma_f32_16x16x32_bf16(Bt[n][k], At[m][k], acc[ai][bj][m][n], 0, 0, 0); __builtin_amdgcn_s_setprio(0); } while (0)
; #define PG8_WAIT_V(n) asm volatile("s_waitcnt vmcnt(" #n ")" ::: "memory")
; #define PG8_WAIT_L(n) asm volatile("s_waitcnt lgkmcnt(" #n ")" ::: "memory")
; #define PG8_BAR __builtin_amdgcn_s_barrier()
; #define PG8_SCHED __builtin_amdgcn_sched_barrier(0)
; template <class Epi, class Sched, bool ALIGN_EPI = false, bool SP2 = false>
; __device__ __forceinline__ void gemm_phase(PG8_LAS unsigned char* lds, const Gemm g, const Sched& S, const Epi& E) {
;     ...
;         for (int t = 0; t < nt; t += 2) {
;             const bool last = (t == nt - 2);
;     ...
;             PG8_LDA(At, 1, 1); PG8_STAGE(PG8_SB(1, 0), b3, voffB); PG8_STAGE(PG8_SB(1, 1), b3 + hstep, voffB); PG8_STAGE(PG8_SA(1, 0), a3, voffA);
;             PG8_WAIT_V(8); PG8_WAIT_L(0); PG8_BAR; PG8_MMA(1, 0, At, B0); PG8_MMA(1, 1, At, B1); PG8_BAR; PG8_SCHED;
	s_add_i32 s12, s85, s63
	v_lshl_add_u64 v[142:143], v[142:143], 0, s[36:37]
	s_mov_b32 m0, s12
	ds_read_b128 v[180:183], v147 offset:49152
	ds_read_b128 v[184:187], v147 offset:50176
	ds_read_b128 v[188:191], v147 offset:51200
	ds_read_b128 v[202:205], v147 offset:52224
	ds_read_b128 v[206:209], v147 offset:53248
	ds_read_b128 v[210:213], v147 offset:54272
	ds_read_b128 v[214:217], v147 offset:55296
	ds_read_b128 v[218:221], v147 offset:56320
	global_load_lds_dwordx4 v[142:143], off
	s_add_i32 m0, s12, 0x2000
	s_add_u32 s12, s58, 0x80080
	v_lshl_add_u64 v[142:143], v[192:193], 0, s[36:37]
	s_addc_u32 s13, s59, 0
	s_add_i32 s58, s92, s63
	global_load_lds_dwordx4 v[142:143], off
	v_lshl_add_u64 v[142:143], s[12:13], 0, v[132:133]
	s_mov_b32 m0, s58
	s_nop 0
	global_load_lds_dwordx4 v[142:143], off
	v_lshl_add_u64 v[142:143], s[12:13], 0, v[136:137]
	s_add_i32 m0, s58, 0x2000
	s_nop 0
	global_load_lds_dwordx4 v[142:143], off
	v_lshl_add_u64 v[142:143], v[222:223], 0, s[36:37]
	s_mov_b32 m0, s68
	s_nop 0
	global_load_lds_dwordx4 v[142:143], off
	v_lshl_add_u64 v[142:143], v[224:225], 0, s[36:37]
	s_mov_b32 m0, s69
	s_nop 0
	global_load_lds_dwordx4 v[142:143], off
	s_waitcnt vmcnt(8)
	s_waitcnt lgkmcnt(0)
	s_barrier
	s_setprio 1
	s_waitcnt lgkmcnt(0)
	v_mfma_f32_16x16x32_bf16 v[60:63], v[148:151], v[180:183], v[60:63]
	v_mfma_f32_16x16x32_bf16 v[56:59], v[156:159], v[180:183], v[56:59]
	v_mfma_f32_16x16x32_bf16 v[52:55], v[148:151], v[188:191], v[52:55]
	v_mfma_f32_16x16x32_bf16 v[44:47], v[156:159], v[188:191], v[44:47]
	v_mfma_f32_16x16x32_bf16 v[36:39], v[148:151], v[206:209], v[36:39]
	v_mfma_f32_16x16x32_bf16 v[28:31], v[156:159], v[206:209], v[28:31]
	v_mfma_f32_16x16x32_bf16 v[20:23], v[148:151], v[214:217], v[20:23]
	v_mfma_f32_16x16x32_bf16 v[12:15], v[156:159], v[214:217], v[12:15]
	v_mfma_f32_16x16x32_bf16 v[60:63], v[152:155], v[184:187], v[60:63]
	v_mfma_f32_16x16x32_bf16 v[56:59], v[160:163], v[184:187], v[56:59]
	v_mfma_f32_16x16x32_bf16 v[52:55], v[152:155], v[202:205], v[52:55]
	v_mfma_f32_16x16x32_bf16 v[44:47], v[160:163], v[202:205], v[44:47]
	v_mfma_f32_16x16x32_bf16 v[36:39], v[152:155], v[210:213], v[36:39]
	v_mfma_f32_16x16x32_bf16 v[28:31], v[160:163], v[210:213], v[28:31]
	v_mfma_f32_16x16x32_bf16 v[20:23], v[152:155], v[218:221], v[20:23]
	v_mfma_f32_16x16x32_bf16 v[12:15], v[160:163], v[218:221], v[12:15]
	v_mfma_f32_16x16x32_bf16 v[48:51], v[164:167], v[180:183], v[48:51]
	v_mfma_f32_16x16x32_bf16 v[40:43], v[172:175], v[180:183], v[40:43]
	v_mfma_f32_16x16x32_bf16 v[32:35], v[164:167], v[188:191], v[32:35]
	v_mfma_f32_16x16x32_bf16 v[24:27], v[172:175], v[188:191], v[24:27]
	v_mfma_f32_16x16x32_bf16 v[16:19], v[164:167], v[206:209], v[16:19]
	v_mfma_f32_16x16x32_bf16 v[8:11], v[172:175], v[206:209], v[8:11]
	v_mfma_f32_16x16x32_bf16 v[4:7], v[164:167], v[214:217], v[4:7]
	v_mfma_f32_16x16x32_bf16 v[0:3], v[172:175], v[214:217], v[0:3]
	v_mfma_f32_16x16x32_bf16 v[48:51], v[168:171], v[184:187], v[48:51]
	v_mfma_f32_16x16x32_bf16 v[40:43], v[176:179], v[184:187], v[40:43]
	v_mfma_f32_16x16x32_bf16 v[32:35], v[168:171], v[202:205], v[32:35]
	v_mfma_f32_16x16x32_bf16 v[24:27], v[176:179], v[202:205], v[24:27]
	v_mfma_f32_16x16x32_bf16 v[16:19], v[168:171], v[210:213], v[16:19]
	v_mfma_f32_16x16x32_bf16 v[8:11], v[176:179], v[210:213], v[8:11]
	v_mfma_f32_16x16x32_bf16 v[4:7], v[168:171], v[218:221], v[4:7]
	v_mfma_f32_16x16x32_bf16 v[0:3], v[176:179], v[218:221], v[0:3]
	s_setprio 0
	s_barrier
	s_add_i32 s84, s84, 2
	s_add_u32 s72, s72, 0x100
	s_addc_u32 s73, s73, 0
	s_add_u32 s56, s56, 0x100
	s_addc_u32 s57, s57, 0
	s_cmp_gt_u32 s84, 29
	s_cbranch_scc0 .LBB0_147
	s_and_b64 vcc, exec, s[14:15]
	s_cbranch_vccz .LBB0_150
	s_barrier

; #define PG8_STAGE(bufoff, gbase, voff) do { _Pragma("unroll") for (int _i = 0; _i < 2; ++_i) \
;         __builtin_amdgcn_global_load_lds((const unsigned*)((const char*)(gbase) + (voff)[_i]), (PG8_LAS unsigned*)(lds + (bufoff) + ldsw + _i * 8192), 16, 0, 0); } while (0)
; #define PG8_LDA(dst, b, h) do { _Pragma("unroll") for (int m = 0; m < 4; ++m) _Pragma("unroll") for (int k = 0; k < 2; ++k) dst[m][k] = *(const PG8_LAS bf16x8*)(lds + PG8_SA(b, h) + aoff + m * 2048 + k * 1024); } while (0)
; #define PG8_LDB(dst, b, h) do { _Pragma("unroll") for (int n = 0; n < 2; ++n) _Pragma("unroll") for (int k = 0; k < 2; ++k) dst[n][k] = *(const PG8_LAS bf16x8*)(lds + PG8_SB(b, h) + boff + n * 2048 + k * 1024); } while (0)
; #define PG8_MMA(ai, bj, At, Bt) do { __builtin_amdgcn_s_setprio(1); _Pragma("unroll") for (int m = 0; m < 4; ++m) _Pragma("unroll") for (int n = 0; n < 2; ++n) _Pragma("unroll") for (int k = 0; k < 2; ++k) \
;         acc[ai][bj][m][n] = __builtin_amdgcn_mfma_f32_16x16x32_bf16(Bt[n][k], At[m][k], acc[ai][bj][m][n], 0, 0, 0); __builtin_amdgcn_s_setprio(0); } while (0)
; #define PG8_WAIT_V(n) asm volatile("s_waitcnt vmcnt(" #n ")" ::: "memory")
; #define PG8_WAIT_L(n) asm volatile("s_waitcnt lgkmcnt(" #n ")" ::: "memory")
; template <class Epi, class Sched, bool ALIGN_EPI = false, bool SP2 = false>
; __device__ __forceinline__ void gemm_phase(PG8_LAS unsigned char* lds, const Gemm g, const Sched& S, const Epi& E) {
;     ...
;             const bool last = (t == nt - 2);
;             const char* a1 = cA + (size_t)(t + 1) * kstep;
;             const char* a2 = last ? nA : cA + (size_t)(t + 2) * kstep; const char* b2 = last ? nB : cB + (size_t)(t + 2) * kstep;
;             const char* a3 = a2 + kstep; const char* b3 = b2 + kstep;
;             if (last && has_next) S.a_ready(nxt);
;             if constexpr (SP2) {
;             PG8_LDB(B0, 0, 0); PG8_LDB(B1, 0, 1); PG8_SCHED; PG8_LDA(At, 0, 0); PG8_STAGE(PG8_SA(1, 1), a1 + hstep, voffA);
;             PG8_WAIT_V(8); PG8_WAIT_L(0); PG8_BAR; PG8_MMA(0, 0, At, B0); PG8_MMA(0, 1, At, B1); PG8_BAR; PG8_SCHED;
;             PG8_LDA(At, 0, 1); PG8_STAGE(PG8_SB(0, 0), b2, voffB); PG8_STAGE(PG8_SB(0, 1), b2 + hstep, voffB); PG8_STAGE(PG8_SA(0, 0), a2, voffA);
;             PG8_WAIT_V(8); PG8_WAIT_L(0); PG8_BAR; PG8_MMA(1, 0, At, B0); PG8_MMA(1, 1, At, B1); PG8_BAR; PG8_SCHED;
.LBB0_175:
	s_add_u32 s12, s42, 0xfff80080
	s_addc_u32 s13, s43, -1
	s_add_i32 vcc_lo, 0, 0x10000
	s_cmp_eq_u32 s55, 28
	s_cselect_b32 s65, s10, s13
	s_cselect_b32 s64, s11, s12
	v_add_u32_e32 v148, vcc_lo, v150
	s_cselect_b32 s63, s5, s19
	s_cselect_b32 s62, s15, s18
	s_add_i32 vcc_hi, 0, 0x14000
	ds_read_b128 v[144:147], v148
	ds_read_b128 v[154:157], v148 offset:1024
	ds_read_b128 v[158:161], v148 offset:2048
	ds_read_b128 v[162:165], v148 offset:3072
	v_add_u32_e32 v148, vcc_hi, v150
	ds_read_b128 v[166:169], v148
	ds_read_b128 v[170:173], v148 offset:1024
	ds_read_b128 v[174:177], v148 offset:2048
	ds_read_b128 v[178:181], v148 offset:3072
	v_lshl_add_u64 v[222:223], s[42:43], 0, v[142:143]
	s_add_i32 m0, s61, 0xc000
	ds_read_b128 v[182:185], v153
	ds_read_b128 v[186:189], v153 offset:1024
	ds_read_b128 v[190:193], v153 offset:2048
	ds_read_b128 v[202:205], v153 offset:3072
	ds_read_b128 v[206:209], v153 offset:4096
	ds_read_b128 v[210:213], v153 offset:5120
	ds_read_b128 v[214:217], v153 offset:6144
	ds_read_b128 v[218:221], v153 offset:7168
	global_load_lds_dwordx4 v[222:223], off
	v_lshl_add_u64 v[222:223], s[42:43], 0, v[140:141]
	s_add_i32 m0, s61, 0xe000
	s_nop 0
	global_load_lds_dwordx4 v[222:223], off
	s_waitcnt vmcnt(8)
	s_waitcnt lgkmcnt(0)
	s_barrier
	s_setprio 1
	s_waitcnt lgkmcnt(0)
	v_mfma_f32_16x16x32_bf16 v[126:129], v[144:147], v[182:185], v[126:129]
	v_mfma_f32_16x16x32_bf16 v[122:125], v[158:161], v[182:185], v[122:125]
	v_mfma_f32_16x16x32_bf16 v[110:113], v[144:147], v[190:193], v[110:113]
	v_mfma_f32_16x16x32_bf16 v[106:109], v[158:161], v[190:193], v[106:109]
	v_mfma_f32_16x16x32_bf16 v[92:95], v[144:147], v[206:209], v[92:95]
	v_mfma_f32_16x16x32_bf16 v[88:91], v[158:161], v[206:209], v[88:91]
	v_mfma_f32_16x16x32_bf16 v[76:79], v[144:147], v[214:217], v[76:79]
	v_mfma_f32_16x16x32_bf16 v[72:75], v[158:161], v[214:217], v[72:75]
	v_mfma_f32_16x16x32_bf16 v[126:129], v[154:157], v[186:189], v[126:129]
	v_mfma_f32_16x16x32_bf16 v[122:125], v[162:165], v[186:189], v[122:125]
	v_mfma_f32_16x16x32_bf16 v[110:113], v[154:157], v[202:205], v[110:113]
	v_mfma_f32_16x16x32_bf16 v[106:109], v[162:165], v[202:205], v[106:109]
	v_mfma_f32_16x16x32_bf16 v[92:95], v[154:157], v[210:213], v[92:95]
	v_mfma_f32_16x16x32_bf16 v[88:91], v[162:165], v[210:213], v[88:91]
	v_mfma_f32_16x16x32_bf16 v[76:79], v[154:157], v[218:221], v[76:79]
	v_mfma_f32_16x16x32_bf16 v[72:75], v[162:165], v[218:221], v[72:75]
	v_mfma_f32_16x16x32_bf16 v[118:121], v[166:169], v[182:185], v[118:121]
	v_mfma_f32_16x16x32_bf16 v[114:117], v[174:177], v[182:185], v[114:117]
	v_mfma_f32_16x16x32_bf16 v[102:105], v[166:169], v[190:193], v[102:105]
	v_mfma_f32_16x16x32_bf16 v[98:101], v[174:177], v[190:193], v[98:101]
	v_mfma_f32_16x16x32_bf16 v[84:87], v[166:169], v[206:209], v[84:87]
	v_mfma_f32_16x16x32_bf16 v[80:83], v[174:177], v[206:209], v[80:83]
	v_mfma_f32_16x16x32_bf16 v[68:71], v[166:169], v[214:217], v[68:71]
	v_mfma_f32_16x16x32_bf16 v[64:67], v[174:177], v[214:217], v[64:67]
	v_mfma_f32_16x16x32_bf16 v[118:121], v[170:173], v[186:189], v[118:121]
	v_mfma_f32_16x16x32_bf16 v[114:117], v[178:181], v[186:189], v[114:117]
	v_mfma_f32_16x16x32_bf16 v[102:105], v[170:173], v[202:205], v[102:105]
	v_mfma_f32_16x16x32_bf16 v[98:101], v[178:181], v[202:205], v[98:101]
	v_mfma_f32_16x16x32_bf16 v[84:87], v[170:173], v[210:213], v[84:87]
	v_mfma_f32_16x16x32_bf16 v[80:83], v[178:181], v[210:213], v[80:83]
	v_mfma_f32_16x16x32_bf16 v[68:71], v[170:173], v[218:221], v[68:71]
	v_mfma_f32_16x16x32_bf16 v[64:67], v[178:181], v[218:221], v[64:67]
	s_setprio 0
	s_barrier
	s_add_i32 s12, vcc_lo, s70
	v_lshl_add_u64 v[222:223], s[62:63], 0, v[132:133]
	s_mov_b32 m0, s12
	ds_read_b128 v[182:185], v153 offset:16384
	ds_read_b128 v[186:189], v153 offset:17408
	ds_read_b128 v[190:193], v153 offset:18432
	ds_read_b128 v[202:205], v153 offset:19456
	ds_read_b128 v[206:209], v153 offset:20480
	ds_read_b128 v[210:213], v153 offset:21504
	ds_read_b128 v[214:217], v153 offset:22528
	ds_read_b128 v[218:221], v153 offset:23552
	global_load_lds_dwordx4 v[222:223], off
	s_add_i32 m0, s12, 0x2000
	s_add_u32 s12, s62, 0x80000
	v_lshl_add_u64 v[224:225], s[62:63], 0, v[136:137]
	s_addc_u32 s13, s63, 0
	s_add_i32 vcc_lo, vcc_hi, s70
	global_load_lds_dwordx4 v[224:225], off
	v_lshl_add_u64 v[226:227], s[12:13], 0, v[132:133]
	s_mov_b32 m0, vcc_lo
	v_lshl_add_u64 v[228:229], s[64:65], 0, v[134:135]
	global_load_lds_dwordx4 v[226:227], off
	v_lshl_add_u64 v[226:227], s[12:13], 0, v[136:137]
	s_add_i32 m0, vcc_lo, 0x2000
	s_nop 0
	global_load_lds_dwordx4 v[226:227], off
	v_lshl_add_u64 v[226:227], s[64:65], 0, v[130:131]
	s_mov_b32 m0, s61
	s_nop 0
	global_load_lds_dwordx4 v[226:227], off
	s_mov_b32 m0, s72
	s_nop 0
	global_load_lds_dwordx4 v[228:229], off
	s_waitcnt vmcnt(8)
	s_waitcnt lgkmcnt(0)
	s_barrier
; #define PG8_STAGE(bufoff, gbase, voff) do { _Pragma("unroll") for (int _i = 0; _i < 2; ++_i) \
;         __builtin_amdgcn_global_load_lds((const unsigned*)((const char*)(gbase) + (voff)[_i]), (PG8_LAS unsigned*)(lds + (bufoff) + ldsw + _i * 8192), 16, 0, 0); } while (0)
; #define PG8_LDA(dst, b, h) do { _Pragma("unroll") for (int m = 0; m < 4; ++m) _Pragma("unroll") for (int k = 0; k < 2; ++k) dst[m][k] = *(const PG8_LAS bf16x8*)(lds + PG8_SA(b, h) + aoff + m * 2048 + k * 1024); } while (0)
; #define PG8_LDB(dst, b, h) do { _Pragma("unroll") for (int n = 0; n < 2; ++n) _Pragma("unroll") for (int k = 0; k < 2; ++k) dst[n][k] = *(const PG8_LAS bf16x8*)(lds + PG8_SB(b, h) + boff + n * 2048 + k * 1024); } while (0)
; #define PG8_MMA(ai, bj, At, Bt) do { __builtin_amdgcn_s_setprio(1); _Pragma("unroll") for (int m = 0; m < 4; ++m) _Pragma("unroll") for (int n = 0; n < 2; ++n) _Pragma("unroll") for (int k = 0; k < 2; ++k) \
;         acc[ai][bj][m][n] = __builtin_amdgcn_mfma_f32_16x16x32_bf16(Bt[n][k], At[m][k], acc[ai][bj][m][n], 0, 0, 0); __builtin_amdgcn_s_setprio(0); } while (0)
; #define PG8_WAIT_V(n) asm volatile("s_waitcnt vmcnt(" #n ")" ::: "memory")
; #define PG8_WAIT_L(n) asm volatile("s_waitcnt lgkmcnt(" #n ")" ::: "memory")
; #define PG8_BAR __builtin_amdgcn_s_barrier()
; #define PG8_SCHED __builtin_amdgcn_sched_barrier(0)
; template <class Epi, class Sched, bool ALIGN_EPI = false, bool SP2 = false>
; __device__ __forceinline__ void gemm_phase(PG8_LAS unsigned char* lds, const Gemm g, const Sched& S, const Epi& E) {
;     ...
;             PG8_WAIT_V(8); PG8_WAIT_L(0); PG8_BAR; PG8_MMA(1, 0, At, B0); PG8_MMA(1, 1, At, B1); PG8_BAR; PG8_SCHED;
;             PG8_LDB(B0, 1, 0); PG8_LDB(B1, 1, 1); PG8_SCHED; PG8_LDA(At, 1, 0); PG8_STAGE(PG8_SA(0, 1), a2 + hstep, voffA);
;             PG8_WAIT_V(8); PG8_WAIT_L(0); PG8_BAR; PG8_MMA(0, 0, At, B0); PG8_MMA(0, 1, At, B1); PG8_BAR; PG8_SCHED;
	s_setprio 1
	s_waitcnt lgkmcnt(0)
	v_mfma_f32_16x16x32_bf16 v[60:63], v[144:147], v[182:185], v[60:63]
	v_mfma_f32_16x16x32_bf16 v[56:59], v[158:161], v[182:185], v[56:59]
	v_mfma_f32_16x16x32_bf16 v[44:47], v[144:147], v[190:193], v[44:47]
	v_mfma_f32_16x16x32_bf16 v[40:43], v[158:161], v[190:193], v[40:43]
	v_mfma_f32_16x16x32_bf16 v[28:31], v[144:147], v[206:209], v[28:31]
	v_mfma_f32_16x16x32_bf16 v[24:27], v[158:161], v[206:209], v[24:27]
	v_mfma_f32_16x16x32_bf16 v[12:15], v[144:147], v[214:217], v[12:15]
	v_mfma_f32_16x16x32_bf16 v[8:11], v[158:161], v[214:217], v[8:11]
	v_mfma_f32_16x16x32_bf16 v[60:63], v[154:157], v[186:189], v[60:63]
	v_mfma_f32_16x16x32_bf16 v[56:59], v[162:165], v[186:189], v[56:59]
	v_mfma_f32_16x16x32_bf16 v[44:47], v[154:157], v[202:205], v[44:47]
	v_mfma_f32_16x16x32_bf16 v[40:43], v[162:165], v[202:205], v[40:43]
	v_mfma_f32_16x16x32_bf16 v[28:31], v[154:157], v[210:213], v[28:31]
	v_mfma_f32_16x16x32_bf16 v[24:27], v[162:165], v[210:213], v[24:27]
	v_mfma_f32_16x16x32_bf16 v[12:15], v[154:157], v[218:221], v[12:15]
	v_mfma_f32_16x16x32_bf16 v[8:11], v[162:165], v[218:221], v[8:11]
	v_mfma_f32_16x16x32_bf16 v[52:55], v[166:169], v[182:185], v[52:55]
	v_mfma_f32_16x16x32_bf16 v[48:51], v[174:177], v[182:185], v[48:51]
	v_mfma_f32_16x16x32_bf16 v[36:39], v[166:169], v[190:193], v[36:39]
	v_mfma_f32_16x16x32_bf16 v[32:35], v[174:177], v[190:193], v[32:35]
	v_mfma_f32_16x16x32_bf16 v[20:23], v[166:169], v[206:209], v[20:23]
	v_mfma_f32_16x16x32_bf16 v[16:19], v[174:177], v[206:209], v[16:19]
	v_mfma_f32_16x16x32_bf16 v[4:7], v[166:169], v[214:217], v[4:7]
	v_mfma_f32_16x16x32_bf16 v[0:3], v[174:177], v[214:217], v[0:3]
	v_mfma_f32_16x16x32_bf16 v[52:55], v[170:173], v[186:189], v[52:55]
	v_mfma_f32_16x16x32_bf16 v[48:51], v[178:181], v[186:189], v[48:51]
	v_mfma_f32_16x16x32_bf16 v[36:39], v[170:173], v[202:205], v[36:39]
	v_mfma_f32_16x16x32_bf16 v[32:35], v[178:181], v[202:205], v[32:35]
	v_mfma_f32_16x16x32_bf16 v[20:23], v[170:173], v[210:213], v[20:23]
	v_mfma_f32_16x16x32_bf16 v[16:19], v[178:181], v[210:213], v[16:19]
	v_mfma_f32_16x16x32_bf16 v[4:7], v[170:173], v[218:221], v[4:7]
	v_mfma_f32_16x16x32_bf16 v[0:3], v[178:181], v[218:221], v[0:3]
	s_setprio 0
	s_barrier
	s_add_i32 vcc_lo, 0, 0x18000
	v_add_u32_e32 v148, vcc_lo, v150
	s_add_i32 vcc_hi, 0, 0x1c000
	ds_read_b128 v[144:147], v148
	ds_read_b128 v[154:157], v148 offset:1024
	ds_read_b128 v[158:161], v148 offset:2048
	ds_read_b128 v[162:165], v148 offset:3072
	v_add_u32_e32 v148, vcc_hi, v150
	ds_read_b128 v[166:169], v148
	ds_read_b128 v[170:173], v148 offset:1024
	ds_read_b128 v[174:177], v148 offset:2048
	ds_read_b128 v[178:181], v148 offset:3072
	s_add_u32 s12, s64, 0x80000
	s_addc_u32 s13, s65, 0
	s_mov_b32 m0, s73
	v_lshl_add_u64 v[230:231], s[12:13], 0, v[130:131]
	ds_read_b128 v[182:185], v153 offset:32768
	ds_read_b128 v[186:189], v153 offset:33792
	ds_read_b128 v[190:193], v153 offset:34816
	ds_read_b128 v[202:205], v153 offset:35840
	ds_read_b128 v[206:209], v153 offset:36864
	ds_read_b128 v[210:213], v153 offset:37888
	ds_read_b128 v[214:217], v153 offset:38912
	ds_read_b128 v[218:221], v153 offset:39936
	global_load_lds_dwordx4 v[230:231], off
	v_lshl_add_u64 v[230:231], s[12:13], 0, v[134:135]
	s_mov_b32 m0, s84
	s_nop 0
	global_load_lds_dwordx4 v[230:231], off
	s_waitcnt vmcnt(8)
	s_waitcnt lgkmcnt(0)
	s_barrier
	s_setprio 1
	s_waitcnt lgkmcnt(0)
	v_mfma_f32_16x16x32_bf16 v[126:129], v[144:147], v[182:185], v[126:129]
	v_mfma_f32_16x16x32_bf16 v[122:125], v[158:161], v[182:185], v[122:125]
	v_mfma_f32_16x16x32_bf16 v[110:113], v[144:147], v[190:193], v[110:113]
	v_mfma_f32_16x16x32_bf16 v[106:109], v[158:161], v[190:193], v[106:109]
	v_mfma_f32_16x16x32_bf16 v[92:95], v[144:147], v[206:209], v[92:95]
	v_mfma_f32_16x16x32_bf16 v[88:91], v[158:161], v[206:209], v[88:91]
	v_mfma_f32_16x16x32_bf16 v[76:79], v[144:147], v[214:217], v[76:79]
	v_mfma_f32_16x16x32_bf16 v[72:75], v[158:161], v[214:217], v[72:75]
	v_mfma_f32_16x16x32_bf16 v[126:129], v[154:157], v[186:189], v[126:129]
	v_mfma_f32_16x16x32_bf16 v[122:125], v[162:165], v[186:189], v[122:125]
	v_mfma_f32_16x16x32_bf16 v[110:113], v[154:157], v[202:205], v[110:113]
	v_mfma_f32_16x16x32_bf16 v[106:109], v[162:165], v[202:205], v[106:109]
	v_mfma_f32_16x16x32_bf16 v[92:95], v[154:157], v[210:213], v[92:95]
	v_mfma_f32_16x16x32_bf16 v[88:91], v[162:165], v[210:213], v[88:91]
	v_mfma_f32_16x16x32_bf16 v[76:79], v[154:157], v[218:221], v[76:79]
	v_mfma_f32_16x16x32_bf16 v[72:75], v[162:165], v[218:221], v[72:75]
	v_mfma_f32_16x16x32_bf16 v[118:121], v[166:169], v[182:185], v[118:121]
	v_mfma_f32_16x16x32_bf16 v[114:117], v[174:177], v[182:185], v[114:117]
	v_mfma_f32_16x16x32_bf16 v[102:105], v[166:169], v[190:193], v[102:105]
	v_mfma_f32_16x16x32_bf16 v[98:101], v[174:177], v[190:193], v[98:101]
	v_mfma_f32_16x16x32_bf16 v[84:87], v[166:169], v[206:209], v[84:87]
	v_mfma_f32_16x16x32_bf16 v[80:83], v[174:177], v[206:209], v[80:83]
	v_mfma_f32_16x16x32_bf16 v[68:71], v[166:169], v[214:217], v[68:71]
	v_mfma_f32_16x16x32_bf16 v[64:67], v[174:177], v[214:217], v[64:67]
	v_mfma_f32_16x16x32_bf16 v[118:121], v[170:173], v[186:189], v[118:121]
	v_mfma_f32_16x16x32_bf16 v[114:117], v[178:181], v[186:189], v[114:117]
	v_mfma_f32_16x16x32_bf16 v[102:105], v[170:173], v[202:205], v[102:105]
	v_mfma_f32_16x16x32_bf16 v[98:101], v[178:181], v[202:205], v[98:101]
	v_mfma_f32_16x16x32_bf16 v[84:87], v[170:173], v[210:213], v[84:87]
	v_mfma_f32_16x16x32_bf16 v[80:83], v[178:181], v[210:213], v[80:83]
	v_mfma_f32_16x16x32_bf16 v[68:71], v[170:173], v[218:221], v[68:71]
	v_mfma_f32_16x16x32_bf16 v[64:67], v[178:181], v[218:221], v[64:67]
	s_setprio 0
	s_barrier
; #define PG8_STAGE(bufoff, gbase, voff) do { _Pragma("unroll") for (int _i = 0; _i < 2; ++_i) \
;         __builtin_amdgcn_global_load_lds((const unsigned*)((const char*)(gbase) + (voff)[_i]), (PG8_LAS unsigned*)(lds + (bufoff) + ldsw + _i * 8192), 16, 0, 0); } while (0)
; #define PG8_LDA(dst, b, h) do { _Pragma("unroll") for (int m = 0; m < 4; ++m) _Pragma("unroll") for (int k = 0; k < 2; ++k) dst[m][k] = *(const PG8_LAS bf16x8*)(lds + PG8_SA(b, h) + aoff + m * 2048 + k * 1024); } while (0)
; #define PG8_MMA(ai, bj, At, Bt) do { __builtin_amdgcn_s_setprio(1); _Pragma("unroll") for (int m = 0; m < 4; ++m) _Pragma("unroll") for (int n = 0; n < 2; ++n) _Pragma("unroll") for (int k = 0; k < 2; ++k) \
;         acc[ai][bj][m][n] = __builtin_amdgcn_mfma_f32_16x16x32_bf16(Bt[n][k], At[m][k], acc[ai][bj][m][n], 0, 0, 0); __builtin_amdgcn_s_setprio(0); } while (0)
; #define PG8_WAIT_V(n) asm volatile("s_waitcnt vmcnt(" #n ")" ::: "memory")
; #define PG8_WAIT_L(n) asm volatile("s_waitcnt lgkmcnt(" #n ")" ::: "memory")
; #define PG8_BAR __builtin_amdgcn_s_barrier()
; #define PG8_SCHED __builtin_amdgcn_sched_barrier(0)
; template <class Epi, class Sched, bool ALIGN_EPI = false, bool SP2 = false>
; __device__ __forceinline__ void gemm_phase(PG8_LAS unsigned char* lds, const Gemm g, const Sched& S, const Epi& E) {
;     ...
;         for (int t = 0; t < nt; t += 2) {
;             const bool last = (t == nt - 2);
;     ...
;             PG8_LDA(At, 1, 1); PG8_STAGE(PG8_SB(1, 0), b3, voffB); PG8_STAGE(PG8_SB(1, 1), b3 + hstep, voffB); PG8_STAGE(PG8_SA(1, 0), a3, voffA);
;             PG8_WAIT_V(8); PG8_WAIT_L(0); PG8_BAR; PG8_MMA(1, 0, At, B0); PG8_MMA(1, 1, At, B1); PG8_BAR; PG8_SCHED;
	s_add_i32 s12, vcc_lo, s70
	v_lshl_add_u64 v[222:223], v[222:223], 0, s[36:37]
	s_mov_b32 m0, s12
	ds_read_b128 v[182:185], v153 offset:49152
	ds_read_b128 v[186:189], v153 offset:50176
	ds_read_b128 v[190:193], v153 offset:51200
	ds_read_b128 v[202:205], v153 offset:52224
	ds_read_b128 v[206:209], v153 offset:53248
	ds_read_b128 v[210:213], v153 offset:54272
	ds_read_b128 v[214:217], v153 offset:55296
	ds_read_b128 v[218:221], v153 offset:56320
	global_load_lds_dwordx4 v[222:223], off
	s_add_i32 m0, s12, 0x2000
	s_add_u32 s12, s62, 0x80080
	v_lshl_add_u64 v[222:223], v[224:225], 0, s[36:37]
	s_addc_u32 s13, s63, 0
	s_add_i32 s62, vcc_hi, s70
	global_load_lds_dwordx4 v[222:223], off
	v_lshl_add_u64 v[222:223], s[12:13], 0, v[132:133]
	s_mov_b32 m0, s62
	s_nop 0
	global_load_lds_dwordx4 v[222:223], off
	v_lshl_add_u64 v[222:223], s[12:13], 0, v[136:137]
	s_add_i32 m0, s62, 0x2000
	s_nop 0
	global_load_lds_dwordx4 v[222:223], off
	v_lshl_add_u64 v[222:223], v[226:227], 0, s[36:37]
	s_mov_b32 m0, s85
	s_nop 0
	global_load_lds_dwordx4 v[222:223], off
	v_lshl_add_u64 v[222:223], v[228:229], 0, s[36:37]
	s_mov_b32 m0, s92
	s_nop 0
	global_load_lds_dwordx4 v[222:223], off
	s_waitcnt vmcnt(8)
	s_waitcnt lgkmcnt(0)
	s_barrier
	s_setprio 1
	s_waitcnt lgkmcnt(0)
	v_mfma_f32_16x16x32_bf16 v[60:63], v[144:147], v[182:185], v[60:63]
	v_mfma_f32_16x16x32_bf16 v[56:59], v[158:161], v[182:185], v[56:59]
	v_mfma_f32_16x16x32_bf16 v[44:47], v[144:147], v[190:193], v[44:47]
	v_mfma_f32_16x16x32_bf16 v[40:43], v[158:161], v[190:193], v[40:43]
	v_mfma_f32_16x16x32_bf16 v[28:31], v[144:147], v[206:209], v[28:31]
	v_mfma_f32_16x16x32_bf16 v[24:27], v[158:161], v[206:209], v[24:27]
	v_mfma_f32_16x16x32_bf16 v[12:15], v[144:147], v[214:217], v[12:15]
	v_mfma_f32_16x16x32_bf16 v[8:11], v[158:161], v[214:217], v[8:11]
	v_mfma_f32_16x16x32_bf16 v[60:63], v[154:157], v[186:189], v[60:63]
	v_mfma_f32_16x16x32_bf16 v[56:59], v[162:165], v[186:189], v[56:59]
	v_mfma_f32_16x16x32_bf16 v[44:47], v[154:157], v[202:205], v[44:47]
	v_mfma_f32_16x16x32_bf16 v[40:43], v[162:165], v[202:205], v[40:43]
	v_mfma_f32_16x16x32_bf16 v[28:31], v[154:157], v[210:213], v[28:31]
	v_mfma_f32_16x16x32_bf16 v[24:27], v[162:165], v[210:213], v[24:27]
	v_mfma_f32_16x16x32_bf16 v[12:15], v[154:157], v[218:221], v[12:15]
	v_mfma_f32_16x16x32_bf16 v[8:11], v[162:165], v[218:221], v[8:11]
	v_mfma_f32_16x16x32_bf16 v[52:55], v[166:169], v[182:185], v[52:55]
	v_mfma_f32_16x16x32_bf16 v[48:51], v[174:177], v[182:185], v[48:51]
	v_mfma_f32_16x16x32_bf16 v[36:39], v[166:169], v[190:193], v[36:39]
	v_mfma_f32_16x16x32_bf16 v[32:35], v[174:177], v[190:193], v[32:35]
	v_mfma_f32_16x16x32_bf16 v[20:23], v[166:169], v[206:209], v[20:23]
	v_mfma_f32_16x16x32_bf16 v[16:19], v[174:177], v[206:209], v[16:19]
	v_mfma_f32_16x16x32_bf16 v[4:7], v[166:169], v[214:217], v[4:7]
	v_mfma_f32_16x16x32_bf16 v[0:3], v[174:177], v[214:217], v[0:3]
	v_mfma_f32_16x16x32_bf16 v[52:55], v[170:173], v[186:189], v[52:55]
	v_mfma_f32_16x16x32_bf16 v[48:51], v[178:181], v[186:189], v[48:51]
	v_mfma_f32_16x16x32_bf16 v[36:39], v[170:173], v[202:205], v[36:39]
	v_mfma_f32_16x16x32_bf16 v[32:35], v[178:181], v[202:205], v[32:35]
	v_mfma_f32_16x16x32_bf16 v[20:23], v[170:173], v[210:213], v[20:23]
	v_mfma_f32_16x16x32_bf16 v[16:19], v[178:181], v[210:213], v[16:19]
	v_mfma_f32_16x16x32_bf16 v[4:7], v[170:173], v[218:221], v[4:7]
	v_mfma_f32_16x16x32_bf16 v[0:3], v[178:181], v[218:221], v[0:3]
	s_setprio 0
	s_barrier
	s_add_i32 s55, s55, 2
	s_add_u32 s18, s18, 0x100
	s_addc_u32 s19, s19, 0
	s_add_u32 s42, s42, 0x100
	s_addc_u32 s43, s43, 0
	s_cmp_gt_u32 s55, 29
	s_cbranch_scc0 .LBB0_175
	s_and_b64 vcc, exec, s[0:1]
	s_cbranch_vccz .LBB0_178
	s_barrier

; #define PG8_STAGE(bufoff, gbase, voff) do { _Pragma("unroll") for (int _i = 0; _i < 2; ++_i) \
;         __builtin_amdgcn_global_load_lds((const unsigned*)((const char*)(gbase) + (voff)[_i]), (PG8_LAS unsigned*)(lds + (bufoff) + ldsw + _i * 8192), 16, 0, 0); } while (0)
; #define PG8_LDA(dst, b, h) do { _Pragma("unroll") for (int m = 0; m < 4; ++m) _Pragma("unroll") for (int k = 0; k < 2; ++k) dst[m][k] = *(const PG8_LAS bf16x8*)(lds + PG8_SA(b, h) + aoff + m * 2048 + k * 1024); } while (0)
; #define PG8_LDB(dst, b, h) do { _Pragma("unroll") for (int n = 0; n < 2; ++n) _Pragma("unroll") for (int k = 0; k < 2; ++k) dst[n][k] = *(const PG8_LAS bf16x8*)(lds + PG8_SB(b, h) + boff + n * 2048 + k * 1024); } while (0)
; #define PG8_MMA(ai, bj, At, Bt) do { __builtin_amdgcn_s_setprio(1); _Pragma("unroll") for (int m = 0; m < 4; ++m) _Pragma("unroll") for (int n = 0; n < 2; ++n) _Pragma("unroll") for (int k = 0; k < 2; ++k) \
;         acc[ai][bj][m][n] = __builtin_amdgcn_mfma_f32_16x16x32_bf16(Bt[n][k], At[m][k], acc[ai][bj][m][n], 0, 0, 0); __builtin_amdgcn_s_setprio(0); } while (0)
; #define PG8_WAIT_V(n) asm volatile("s_waitcnt vmcnt(" #n ")" ::: "memory")
; #define PG8_WAIT_L(n) asm volatile("s_waitcnt lgkmcnt(" #n ")" ::: "memory")
; template <class Epi, class Sched, bool ALIGN_EPI = false, bool SP2 = false>
; __device__ __forceinline__ void gemm_phase(PG8_LAS unsigned char* lds, const Gemm g, const Sched& S, const Epi& E) {
;     ...
;             const bool last = (t == nt - 2);
;             const char* a1 = cA + (size_t)(t + 1) * kstep;
;             const char* a2 = last ? nA : cA + (size_t)(t + 2) * kstep; const char* b2 = last ? nB : cB + (size_t)(t + 2) * kstep;
;             const char* a3 = a2 + kstep; const char* b3 = b2 + kstep;
;             if (last && has_next) S.a_ready(nxt);
;             if constexpr (SP2) {
;             PG8_LDB(B0, 0, 0); PG8_LDB(B1, 0, 1); PG8_SCHED; PG8_LDA(At, 0, 0); PG8_STAGE(PG8_SA(1, 1), a1 + hstep, voffA);
;             PG8_WAIT_V(8); PG8_WAIT_L(0); PG8_BAR; PG8_MMA(0, 0, At, B0); PG8_MMA(0, 1, At, B1); PG8_BAR; PG8_SCHED;
;             PG8_LDA(At, 0, 1); PG8_STAGE(PG8_SB(0, 0), b2, voffB); PG8_STAGE(PG8_SB(0, 1), b2 + hstep, voffB); PG8_STAGE(PG8_SA(0, 0), a2, voffA);
;             PG8_WAIT_V(8); PG8_WAIT_L(0); PG8_BAR; PG8_MMA(1, 0, At, B0); PG8_MMA(1, 1, At, B1); PG8_BAR; PG8_SCHED;
.LBB0_236:
	s_add_u32 s12, s42, 0xfff80080
	s_addc_u32 s13, s43, -1
	s_add_i32 s73, 0, 0x10000
	s_cmp_eq_u32 s51, 28
	s_cselect_b32 s61, s10, s13
	s_cselect_b32 s60, s11, s12
	v_add_u32_e32 v148, s73, v149
	s_cselect_b32 s59, s5, s19
	s_cselect_b32 s58, s15, s18
	s_add_i32 s84, 0, 0x14000
	ds_read_b128 v[144:147], v148
	ds_read_b128 v[154:157], v148 offset:1024
	ds_read_b128 v[158:161], v148 offset:2048
	ds_read_b128 v[162:165], v148 offset:3072
	v_add_u32_e32 v148, s84, v149
	ds_read_b128 v[166:169], v148
	ds_read_b128 v[170:173], v148 offset:1024
	ds_read_b128 v[174:177], v148 offset:2048
	ds_read_b128 v[178:181], v148 offset:3072
	v_lshl_add_u64 v[222:223], s[42:43], 0, v[142:143]
	s_add_i32 m0, s57, 0xc000
	ds_read_b128 v[182:185], v152
	ds_read_b128 v[186:189], v152 offset:1024
	ds_read_b128 v[190:193], v152 offset:2048
	ds_read_b128 v[202:205], v152 offset:3072
	ds_read_b128 v[206:209], v152 offset:4096
	ds_read_b128 v[210:213], v152 offset:5120
	ds_read_b128 v[214:217], v152 offset:6144
	ds_read_b128 v[218:221], v152 offset:7168
	global_load_lds_dwordx4 v[222:223], off
	v_lshl_add_u64 v[222:223], s[42:43], 0, v[140:141]
	s_add_i32 m0, s57, 0xe000
	s_nop 0
	global_load_lds_dwordx4 v[222:223], off
	s_waitcnt vmcnt(8)
	s_waitcnt lgkmcnt(0)
	s_barrier
	s_setprio 1
	s_waitcnt lgkmcnt(0)
	v_mfma_f32_16x16x32_bf16 v[126:129], v[144:147], v[182:185], v[126:129]
	v_mfma_f32_16x16x32_bf16 v[122:125], v[158:161], v[182:185], v[122:125]
	v_mfma_f32_16x16x32_bf16 v[110:113], v[144:147], v[190:193], v[110:113]
	v_mfma_f32_16x16x32_bf16 v[106:109], v[158:161], v[190:193], v[106:109]
	v_mfma_f32_16x16x32_bf16 v[92:95], v[144:147], v[206:209], v[92:95]
	v_mfma_f32_16x16x32_bf16 v[88:91], v[158:161], v[206:209], v[88:91]
	v_mfma_f32_16x16x32_bf16 v[76:79], v[144:147], v[214:217], v[76:79]
	v_mfma_f32_16x16x32_bf16 v[72:75], v[158:161], v[214:217], v[72:75]
	v_mfma_f32_16x16x32_bf16 v[126:129], v[154:157], v[186:189], v[126:129]
	v_mfma_f32_16x16x32_bf16 v[122:125], v[162:165], v[186:189], v[122:125]
	v_mfma_f32_16x16x32_bf16 v[110:113], v[154:157], v[202:205], v[110:113]
	v_mfma_f32_16x16x32_bf16 v[106:109], v[162:165], v[202:205], v[106:109]
	v_mfma_f32_16x16x32_bf16 v[92:95], v[154:157], v[210:213], v[92:95]
	v_mfma_f32_16x16x32_bf16 v[88:91], v[162:165], v[210:213], v[88:91]
	v_mfma_f32_16x16x32_bf16 v[76:79], v[154:157], v[218:221], v[76:79]
	v_mfma_f32_16x16x32_bf16 v[72:75], v[162:165], v[218:221], v[72:75]
	v_mfma_f32_16x16x32_bf16 v[118:121], v[166:169], v[182:185], v[118:121]
	v_mfma_f32_16x16x32_bf16 v[114:117], v[174:177], v[182:185], v[114:117]
	v_mfma_f32_16x16x32_bf16 v[102:105], v[166:169], v[190:193], v[102:105]
	v_mfma_f32_16x16x32_bf16 v[98:101], v[174:177], v[190:193], v[98:101]
	v_mfma_f32_16x16x32_bf16 v[84:87], v[166:169], v[206:209], v[84:87]
	v_mfma_f32_16x16x32_bf16 v[80:83], v[174:177], v[206:209], v[80:83]
	v_mfma_f32_16x16x32_bf16 v[68:71], v[166:169], v[214:217], v[68:71]
	v_mfma_f32_16x16x32_bf16 v[64:67], v[174:177], v[214:217], v[64:67]
	v_mfma_f32_16x16x32_bf16 v[118:121], v[170:173], v[186:189], v[118:121]
	v_mfma_f32_16x16x32_bf16 v[114:117], v[178:181], v[186:189], v[114:117]
	v_mfma_f32_16x16x32_bf16 v[102:105], v[170:173], v[202:205], v[102:105]
	v_mfma_f32_16x16x32_bf16 v[98:101], v[178:181], v[202:205], v[98:101]
	v_mfma_f32_16x16x32_bf16 v[84:87], v[170:173], v[210:213], v[84:87]
	v_mfma_f32_16x16x32_bf16 v[80:83], v[178:181], v[210:213], v[80:83]
	v_mfma_f32_16x16x32_bf16 v[68:71], v[170:173], v[218:221], v[68:71]
	v_mfma_f32_16x16x32_bf16 v[64:67], v[178:181], v[218:221], v[64:67]
	s_setprio 0
	s_barrier
	s_add_i32 s12, s73, s9
	v_lshl_add_u64 v[222:223], s[58:59], 0, v[132:133]
	s_mov_b32 m0, s12
	ds_read_b128 v[182:185], v152 offset:16384
	ds_read_b128 v[186:189], v152 offset:17408
	ds_read_b128 v[190:193], v152 offset:18432
	ds_read_b128 v[202:205], v152 offset:19456
	ds_read_b128 v[206:209], v152 offset:20480
	ds_read_b128 v[210:213], v152 offset:21504
	ds_read_b128 v[214:217], v152 offset:22528
	ds_read_b128 v[218:221], v152 offset:23552
	global_load_lds_dwordx4 v[222:223], off
	s_add_i32 m0, s12, 0x2000
	s_add_u32 s12, s58, 0x80000
	v_lshl_add_u64 v[224:225], s[58:59], 0, v[136:137]
	s_addc_u32 s13, s59, 0
	s_add_i32 s73, s84, s9
	global_load_lds_dwordx4 v[224:225], off
	v_lshl_add_u64 v[226:227], s[12:13], 0, v[132:133]
	s_mov_b32 m0, s73
	v_lshl_add_u64 v[228:229], s[60:61], 0, v[134:135]
	global_load_lds_dwordx4 v[226:227], off
	v_lshl_add_u64 v[226:227], s[12:13], 0, v[136:137]
	s_add_i32 m0, s73, 0x2000
	s_nop 0
	global_load_lds_dwordx4 v[226:227], off
	v_lshl_add_u64 v[226:227], s[60:61], 0, v[130:131]
	s_mov_b32 m0, s57
	s_nop 0
	global_load_lds_dwordx4 v[226:227], off
	s_mov_b32 m0, s63
	s_nop 0
	global_load_lds_dwordx4 v[228:229], off
	s_waitcnt vmcnt(8)
	s_waitcnt lgkmcnt(0)
	s_barrier
; #define PG8_STAGE(bufoff, gbase, voff) do { _Pragma("unroll") for (int _i = 0; _i < 2; ++_i) \
;         __builtin_amdgcn_global_load_lds((const unsigned*)((const char*)(gbase) + (voff)[_i]), (PG8_LAS unsigned*)(lds + (bufoff) + ldsw + _i * 8192), 16, 0, 0); } while (0)
; #define PG8_LDA(dst, b, h) do { _Pragma("unroll") for (int m = 0; m < 4; ++m) _Pragma("unroll") for (int k = 0; k < 2; ++k) dst[m][k] = *(const PG8_LAS bf16x8*)(lds + PG8_SA(b, h) + aoff + m * 2048 + k * 1024); } while (0)
; #define PG8_LDB(dst, b, h) do { _Pragma("unroll") for (int n = 0; n < 2; ++n) _Pragma("unroll") for (int k = 0; k < 2; ++k) dst[n][k] = *(const PG8_LAS bf16x8*)(lds + PG8_SB(b, h) + boff + n * 2048 + k * 1024); } while (0)
; #define PG8_MMA(ai, bj, At, Bt) do { __builtin_amdgcn_s_setprio(1); _Pragma("unroll") for (int m = 0; m < 4; ++m) _Pragma("unroll") for (int n = 0; n < 2; ++n) _Pragma("unroll") for (int k = 0; k < 2; ++k) \
;         acc[ai][bj][m][n] = __builtin_amdgcn_mfma_f32_16x16x32_bf16(Bt[n][k], At[m][k], acc[ai][bj][m][n], 0, 0, 0); __builtin_amdgcn_s_setprio(0); } while (0)
; #define PG8_WAIT_V(n) asm volatile("s_waitcnt vmcnt(" #n ")" ::: "memory")
; #define PG8_WAIT_L(n) asm volatile("s_waitcnt lgkmcnt(" #n ")" ::: "memory")
; #define PG8_BAR __builtin_amdgcn_s_barrier()
; #define PG8_SCHED __builtin_amdgcn_sched_barrier(0)
; template <class Epi, class Sched, bool ALIGN_EPI = false, bool SP2 = false>
; __device__ __forceinline__ void gemm_phase(PG8_LAS unsigned char* lds, const Gemm g, const Sched& S, const Epi& E) {
;     ...
;             PG8_WAIT_V(8); PG8_WAIT_L(0); PG8_BAR; PG8_MMA(1, 0, At, B0); PG8_MMA(1, 1, At, B1); PG8_BAR; PG8_SCHED;
;             PG8_LDB(B0, 1, 0); PG8_LDB(B1, 1, 1); PG8_SCHED; PG8_LDA(At, 1, 0); PG8_STAGE(PG8_SA(0, 1), a2 + hstep, voffA);
;             PG8_WAIT_V(8); PG8_WAIT_L(0); PG8_BAR; PG8_MMA(0, 0, At, B0); PG8_MMA(0, 1, At, B1); PG8_BAR; PG8_SCHED;
	s_setprio 1
	s_waitcnt lgkmcnt(0)
	v_mfma_f32_16x16x32_bf16 v[60:63], v[144:147], v[182:185], v[60:63]
	v_mfma_f32_16x16x32_bf16 v[56:59], v[158:161], v[182:185], v[56:59]
	v_mfma_f32_16x16x32_bf16 v[44:47], v[144:147], v[190:193], v[44:47]
	v_mfma_f32_16x16x32_bf16 v[40:43], v[158:161], v[190:193], v[40:43]
	v_mfma_f32_16x16x32_bf16 v[28:31], v[144:147], v[206:209], v[28:31]
	v_mfma_f32_16x16x32_bf16 v[24:27], v[158:161], v[206:209], v[24:27]
	v_mfma_f32_16x16x32_bf16 v[12:15], v[144:147], v[214:217], v[12:15]
	v_mfma_f32_16x16x32_bf16 v[8:11], v[158:161], v[214:217], v[8:11]
	v_mfma_f32_16x16x32_bf16 v[60:63], v[154:157], v[186:189], v[60:63]
	v_mfma_f32_16x16x32_bf16 v[56:59], v[162:165], v[186:189], v[56:59]
	v_mfma_f32_16x16x32_bf16 v[44:47], v[154:157], v[202:205], v[44:47]
	v_mfma_f32_16x16x32_bf16 v[40:43], v[162:165], v[202:205], v[40:43]
	v_mfma_f32_16x16x32_bf16 v[28:31], v[154:157], v[210:213], v[28:31]
	v_mfma_f32_16x16x32_bf16 v[24:27], v[162:165], v[210:213], v[24:27]
	v_mfma_f32_16x16x32_bf16 v[12:15], v[154:157], v[218:221], v[12:15]
	v_mfma_f32_16x16x32_bf16 v[8:11], v[162:165], v[218:221], v[8:11]
	v_mfma_f32_16x16x32_bf16 v[52:55], v[166:169], v[182:185], v[52:55]
	v_mfma_f32_16x16x32_bf16 v[48:51], v[174:177], v[182:185], v[48:51]
	v_mfma_f32_16x16x32_bf16 v[36:39], v[166:169], v[190:193], v[36:39]
	v_mfma_f32_16x16x32_bf16 v[32:35], v[174:177], v[190:193], v[32:35]
	v_mfma_f32_16x16x32_bf16 v[20:23], v[166:169], v[206:209], v[20:23]
	v_mfma_f32_16x16x32_bf16 v[16:19], v[174:177], v[206:209], v[16:19]
	v_mfma_f32_16x16x32_bf16 v[4:7], v[166:169], v[214:217], v[4:7]
	v_mfma_f32_16x16x32_bf16 v[0:3], v[174:177], v[214:217], v[0:3]
	v_mfma_f32_16x16x32_bf16 v[52:55], v[170:173], v[186:189], v[52:55]
	v_mfma_f32_16x16x32_bf16 v[48:51], v[178:181], v[186:189], v[48:51]
	v_mfma_f32_16x16x32_bf16 v[36:39], v[170:173], v[202:205], v[36:39]
	v_mfma_f32_16x16x32_bf16 v[32:35], v[178:181], v[202:205], v[32:35]
	v_mfma_f32_16x16x32_bf16 v[20:23], v[170:173], v[210:213], v[20:23]
	v_mfma_f32_16x16x32_bf16 v[16:19], v[178:181], v[210:213], v[16:19]
	v_mfma_f32_16x16x32_bf16 v[4:7], v[170:173], v[218:221], v[4:7]
	v_mfma_f32_16x16x32_bf16 v[0:3], v[178:181], v[218:221], v[0:3]
	s_setprio 0
	s_barrier
	s_add_i32 s73, 0, 0x18000
	v_add_u32_e32 v148, s73, v149
	s_add_i32 s84, 0, 0x1c000
	ds_read_b128 v[144:147], v148
	ds_read_b128 v[154:157], v148 offset:1024
	ds_read_b128 v[158:161], v148 offset:2048
	ds_read_b128 v[162:165], v148 offset:3072
	v_add_u32_e32 v148, s84, v149
	ds_read_b128 v[166:169], v148
	ds_read_b128 v[170:173], v148 offset:1024
	ds_read_b128 v[174:177], v148 offset:2048
	ds_read_b128 v[178:181], v148 offset:3072
	s_add_u32 s12, s60, 0x80000
	s_addc_u32 s13, s61, 0
	s_mov_b32 m0, s64
	v_lshl_add_u64 v[230:231], s[12:13], 0, v[130:131]
	ds_read_b128 v[182:185], v152 offset:32768
	ds_read_b128 v[186:189], v152 offset:33792
	ds_read_b128 v[190:193], v152 offset:34816
	ds_read_b128 v[202:205], v152 offset:35840
	ds_read_b128 v[206:209], v152 offset:36864
	ds_read_b128 v[210:213], v152 offset:37888
	ds_read_b128 v[214:217], v152 offset:38912
	ds_read_b128 v[218:221], v152 offset:39936
	global_load_lds_dwordx4 v[230:231], off
	v_lshl_add_u64 v[230:231], s[12:13], 0, v[134:135]
	s_mov_b32 m0, s65
	s_nop 0
	global_load_lds_dwordx4 v[230:231], off
	s_waitcnt vmcnt(8)
	s_waitcnt lgkmcnt(0)
	s_barrier
	s_setprio 1
	s_waitcnt lgkmcnt(0)
	v_mfma_f32_16x16x32_bf16 v[126:129], v[144:147], v[182:185], v[126:129]
	v_mfma_f32_16x16x32_bf16 v[122:125], v[158:161], v[182:185], v[122:125]
	v_mfma_f32_16x16x32_bf16 v[110:113], v[144:147], v[190:193], v[110:113]
	v_mfma_f32_16x16x32_bf16 v[106:109], v[158:161], v[190:193], v[106:109]
	v_mfma_f32_16x16x32_bf16 v[92:95], v[144:147], v[206:209], v[92:95]
	v_mfma_f32_16x16x32_bf16 v[88:91], v[158:161], v[206:209], v[88:91]
	v_mfma_f32_16x16x32_bf16 v[76:79], v[144:147], v[214:217], v[76:79]
	v_mfma_f32_16x16x32_bf16 v[72:75], v[158:161], v[214:217], v[72:75]
	v_mfma_f32_16x16x32_bf16 v[126:129], v[154:157], v[186:189], v[126:129]
	v_mfma_f32_16x16x32_bf16 v[122:125], v[162:165], v[186:189], v[122:125]
	v_mfma_f32_16x16x32_bf16 v[110:113], v[154:157], v[202:205], v[110:113]
	v_mfma_f32_16x16x32_bf16 v[106:109], v[162:165], v[202:205], v[106:109]
	v_mfma_f32_16x16x32_bf16 v[92:95], v[154:157], v[210:213], v[92:95]
	v_mfma_f32_16x16x32_bf16 v[88:91], v[162:165], v[210:213], v[88:91]
	v_mfma_f32_16x16x32_bf16 v[76:79], v[154:157], v[218:221], v[76:79]
	v_mfma_f32_16x16x32_bf16 v[72:75], v[162:165], v[218:221], v[72:75]
	v_mfma_f32_16x16x32_bf16 v[118:121], v[166:169], v[182:185], v[118:121]
	v_mfma_f32_16x16x32_bf16 v[114:117], v[174:177], v[182:185], v[114:117]
	v_mfma_f32_16x16x32_bf16 v[102:105], v[166:169], v[190:193], v[102:105]
	v_mfma_f32_16x16x32_bf16 v[98:101], v[174:177], v[190:193], v[98:101]
	v_mfma_f32_16x16x32_bf16 v[84:87], v[166:169], v[206:209], v[84:87]
	v_mfma_f32_16x16x32_bf16 v[80:83], v[174:177], v[206:209], v[80:83]
	v_mfma_f32_16x16x32_bf16 v[68:71], v[166:169], v[214:217], v[68:71]
	v_mfma_f32_16x16x32_bf16 v[64:67], v[174:177], v[214:217], v[64:67]
	v_mfma_f32_16x16x32_bf16 v[118:121], v[170:173], v[186:189], v[118:121]
	v_mfma_f32_16x16x32_bf16 v[114:117], v[178:181], v[186:189], v[114:117]
	v_mfma_f32_16x16x32_bf16 v[102:105], v[170:173], v[202:205], v[102:105]
	v_mfma_f32_16x16x32_bf16 v[98:101], v[178:181], v[202:205], v[98:101]
	v_mfma_f32_16x16x32_bf16 v[84:87], v[170:173], v[210:213], v[84:87]
	v_mfma_f32_16x16x32_bf16 v[80:83], v[178:181], v[210:213], v[80:83]
	v_mfma_f32_16x16x32_bf16 v[68:71], v[170:173], v[218:221], v[68:71]
	v_mfma_f32_16x16x32_bf16 v[64:67], v[178:181], v[218:221], v[64:67]
	s_setprio 0
	s_barrier
; #define PG8_STAGE(bufoff, gbase, voff) do { _Pragma("unroll") for (int _i = 0; _i < 2; ++_i) \
;         __builtin_amdgcn_global_load_lds((const unsigned*)((const char*)(gbase) + (voff)[_i]), (PG8_LAS unsigned*)(lds + (bufoff) + ldsw + _i * 8192), 16, 0, 0); } while (0)
; #define PG8_LDA(dst, b, h) do { _Pragma("unroll") for (int m = 0; m < 4; ++m) _Pragma("unroll") for (int k = 0; k < 2; ++k) dst[m][k] = *(const PG8_LAS bf16x8*)(lds + PG8_SA(b, h) + aoff + m * 2048 + k * 1024); } while (0)
; #define PG8_MMA(ai, bj, At, Bt) do { __builtin_amdgcn_s_setprio(1); _Pragma("unroll") for (int m = 0; m < 4; ++m) _Pragma("unroll") for (int n = 0; n < 2; ++n) _Pragma("unroll") for (int k = 0; k < 2; ++k) \
;         acc[ai][bj][m][n] = __builtin_amdgcn_mfma_f32_16x16x32_bf16(Bt[n][k], At[m][k], acc[ai][bj][m][n], 0, 0, 0); __builtin_amdgcn_s_setprio(0); } while (0)
; #define PG8_WAIT_V(n) asm volatile("s_waitcnt vmcnt(" #n ")" ::: "memory")
; #define PG8_WAIT_L(n) asm volatile("s_waitcnt lgkmcnt(" #n ")" ::: "memory")
; #define PG8_BAR __builtin_amdgcn_s_barrier()
; #define PG8_SCHED __builtin_amdgcn_sched_barrier(0)
; template <class Epi, class Sched, bool ALIGN_EPI = false, bool SP2 = false>
; __device__ __forceinline__ void gemm_phase(PG8_LAS unsigned char* lds, const Gemm g, const Sched& S, const Epi& E) {
;     ...
;         for (int t = 0; t < nt; t += 2) {
;             const bool last = (t == nt - 2);
;     ...
;             PG8_LDA(At, 1, 1); PG8_STAGE(PG8_SB(1, 0), b3, voffB); PG8_STAGE(PG8_SB(1, 1), b3 + hstep, voffB); PG8_STAGE(PG8_SA(1, 0), a3, voffA);
;             PG8_WAIT_V(8); PG8_WAIT_L(0); PG8_BAR; PG8_MMA(1, 0, At, B0); PG8_MMA(1, 1, At, B1); PG8_BAR; PG8_SCHED;
	s_add_i32 s12, s73, s9
	v_lshl_add_u64 v[222:223], v[222:223], 0, s[36:37]
	s_mov_b32 m0, s12
	ds_read_b128 v[182:185], v152 offset:49152
	ds_read_b128 v[186:189], v152 offset:50176
	ds_read_b128 v[190:193], v152 offset:51200
	ds_read_b128 v[202:205], v152 offset:52224
	ds_read_b128 v[206:209], v152 offset:53248
	ds_read_b128 v[210:213], v152 offset:54272
	ds_read_b128 v[214:217], v152 offset:55296
	ds_read_b128 v[218:221], v152 offset:56320
	global_load_lds_dwordx4 v[222:223], off
	s_add_i32 m0, s12, 0x2000
	s_add_u32 s12, s58, 0x80080
	v_lshl_add_u64 v[222:223], v[224:225], 0, s[36:37]
	s_addc_u32 s13, s59, 0
	s_add_i32 s58, s84, s9
	global_load_lds_dwordx4 v[222:223], off
	v_lshl_add_u64 v[222:223], s[12:13], 0, v[132:133]
	s_mov_b32 m0, s58
	s_nop 0
	global_load_lds_dwordx4 v[222:223], off
	v_lshl_add_u64 v[222:223], s[12:13], 0, v[136:137]
	s_add_i32 m0, s58, 0x2000
	s_nop 0
	global_load_lds_dwordx4 v[222:223], off
	v_lshl_add_u64 v[222:223], v[226:227], 0, s[36:37]
	s_mov_b32 m0, s70
	s_nop 0
	global_load_lds_dwordx4 v[222:223], off
	v_lshl_add_u64 v[222:223], v[228:229], 0, s[36:37]
	s_mov_b32 m0, s71
	s_nop 0
	global_load_lds_dwordx4 v[222:223], off
	s_waitcnt vmcnt(8)
	s_waitcnt lgkmcnt(0)
	s_barrier
	s_setprio 1
	s_waitcnt lgkmcnt(0)
	v_mfma_f32_16x16x32_bf16 v[60:63], v[144:147], v[182:185], v[60:63]
	v_mfma_f32_16x16x32_bf16 v[56:59], v[158:161], v[182:185], v[56:59]
	v_mfma_f32_16x16x32_bf16 v[44:47], v[144:147], v[190:193], v[44:47]
	v_mfma_f32_16x16x32_bf16 v[40:43], v[158:161], v[190:193], v[40:43]
	v_mfma_f32_16x16x32_bf16 v[28:31], v[144:147], v[206:209], v[28:31]
	v_mfma_f32_16x16x32_bf16 v[24:27], v[158:161], v[206:209], v[24:27]
	v_mfma_f32_16x16x32_bf16 v[12:15], v[144:147], v[214:217], v[12:15]
	v_mfma_f32_16x16x32_bf16 v[8:11], v[158:161], v[214:217], v[8:11]
	v_mfma_f32_16x16x32_bf16 v[60:63], v[154:157], v[186:189], v[60:63]
	v_mfma_f32_16x16x32_bf16 v[56:59], v[162:165], v[186:189], v[56:59]
	v_mfma_f32_16x16x32_bf16 v[44:47], v[154:157], v[202:205], v[44:47]
	v_mfma_f32_16x16x32_bf16 v[40:43], v[162:165], v[202:205], v[40:43]
	v_mfma_f32_16x16x32_bf16 v[28:31], v[154:157], v[210:213], v[28:31]
	v_mfma_f32_16x16x32_bf16 v[24:27], v[162:165], v[210:213], v[24:27]
	v_mfma_f32_16x16x32_bf16 v[12:15], v[154:157], v[218:221], v[12:15]
	v_mfma_f32_16x16x32_bf16 v[8:11], v[162:165], v[218:221], v[8:11]
	v_mfma_f32_16x16x32_bf16 v[52:55], v[166:169], v[182:185], v[52:55]
	v_mfma_f32_16x16x32_bf16 v[48:51], v[174:177], v[182:185], v[48:51]
	v_mfma_f32_16x16x32_bf16 v[36:39], v[166:169], v[190:193], v[36:39]
	v_mfma_f32_16x16x32_bf16 v[32:35], v[174:177], v[190:193], v[32:35]
	v_mfma_f32_16x16x32_bf16 v[20:23], v[166:169], v[206:209], v[20:23]
	v_mfma_f32_16x16x32_bf16 v[16:19], v[174:177], v[206:209], v[16:19]
	v_mfma_f32_16x16x32_bf16 v[4:7], v[166:169], v[214:217], v[4:7]
	v_mfma_f32_16x16x32_bf16 v[0:3], v[174:177], v[214:217], v[0:3]
	v_mfma_f32_16x16x32_bf16 v[52:55], v[170:173], v[186:189], v[52:55]
	v_mfma_f32_16x16x32_bf16 v[48:51], v[178:181], v[186:189], v[48:51]
	v_mfma_f32_16x16x32_bf16 v[36:39], v[170:173], v[202:205], v[36:39]
	v_mfma_f32_16x16x32_bf16 v[32:35], v[178:181], v[202:205], v[32:35]
	v_mfma_f32_16x16x32_bf16 v[20:23], v[170:173], v[210:213], v[20:23]
	v_mfma_f32_16x16x32_bf16 v[16:19], v[178:181], v[210:213], v[16:19]
	v_mfma_f32_16x16x32_bf16 v[4:7], v[170:173], v[218:221], v[4:7]
	v_mfma_f32_16x16x32_bf16 v[0:3], v[178:181], v[218:221], v[0:3]
	s_setprio 0
	s_barrier
	s_add_i32 s51, s51, 2
	s_add_u32 s18, s18, 0x100
	s_addc_u32 s19, s19, 0
	s_add_u32 s42, s42, 0x100
	s_addc_u32 s43, s43, 0
	s_cmp_gt_u32 s51, 29
	s_cbranch_scc0 .LBB0_236
	s_and_b64 vcc, exec, s[0:1]
	s_cbranch_vccz .LBB0_239
	s_barrier

; #define PG8_STAGE(bufoff, gbase, voff) do { _Pragma("unroll") for (int _i = 0; _i < 2; ++_i) \
;         __builtin_amdgcn_global_load_lds((const unsigned*)((const char*)(gbase) + (voff)[_i]), (PG8_LAS unsigned*)(lds + (bufoff) + ldsw + _i * 8192), 16, 0, 0); } while (0)
; #define PG8_LDA(dst, b, h) do { _Pragma("unroll") for (int m = 0; m < 4; ++m) _Pragma("unroll") for (int k = 0; k < 2; ++k) dst[m][k] = *(const PG8_LAS bf16x8*)(lds + PG8_SA(b, h) + aoff + m * 2048 + k * 1024); } while (0)
; #define PG8_LDB(dst, b, h) do { _Pragma("unroll") for (int n = 0; n < 2; ++n) _Pragma("unroll") for (int k = 0; k < 2; ++k) dst[n][k] = *(const PG8_LAS bf16x8*)(lds + PG8_SB(b, h) + boff + n * 2048 + k * 1024); } while (0)
; #define PG8_MMA(ai, bj, At, Bt) do { __builtin_amdgcn_s_setprio(1); _Pragma("unroll") for (int m = 0; m < 4; ++m) _Pragma("unroll") for (int n = 0; n < 2; ++n) _Pragma("unroll") for (int k = 0; k < 2; ++k) \
;         acc[ai][bj][m][n] = __builtin_amdgcn_mfma_f32_16x16x32_bf16(Bt[n][k], At[m][k], acc[ai][bj][m][n], 0, 0, 0); __builtin_amdgcn_s_setprio(0); } while (0)
; #define PG8_WAIT_V(n) asm volatile("s_waitcnt vmcnt(" #n ")" ::: "memory")
; #define PG8_WAIT_L(n) asm volatile("s_waitcnt lgkmcnt(" #n ")" ::: "memory")
; template <class Epi, class Sched, bool ALIGN_EPI = false, bool SP2 = false>
; __device__ __forceinline__ void gemm_phase(PG8_LAS unsigned char* lds, const Gemm g, const Sched& S, const Epi& E) {
;     ...
;             const bool last = (t == nt - 2);
;             const char* a1 = cA + (size_t)(t + 1) * kstep;
;             const char* a2 = last ? nA : cA + (size_t)(t + 2) * kstep; const char* b2 = last ? nB : cB + (size_t)(t + 2) * kstep;
;             const char* a3 = a2 + kstep; const char* b3 = b2 + kstep;
;             if (last && has_next) S.a_ready(nxt);
;             if constexpr (SP2) {
;             PG8_LDB(B0, 0, 0); PG8_LDB(B1, 0, 1); PG8_SCHED; PG8_LDA(At, 0, 0); PG8_STAGE(PG8_SA(1, 1), a1 + hstep, voffA);
;             PG8_WAIT_V(8); PG8_WAIT_L(0); PG8_BAR; PG8_MMA(0, 0, At, B0); PG8_MMA(0, 1, At, B1); PG8_BAR; PG8_SCHED;
;             PG8_LDA(At, 0, 1); PG8_STAGE(PG8_SB(0, 0), b2, voffB); PG8_STAGE(PG8_SB(0, 1), b2 + hstep, voffB); PG8_STAGE(PG8_SA(0, 0), a2, voffA);
;             PG8_WAIT_V(8); PG8_WAIT_L(0); PG8_BAR; PG8_MMA(1, 0, At, B0); PG8_MMA(1, 1, At, B1); PG8_BAR; PG8_SCHED;
.LBB0_892:
	s_add_u32 s12, s58, 0xfff80080
	s_addc_u32 s13, s59, -1
	s_add_i32 s84, 0, 0x10000
	s_cmp_eq_u32 s73, 28
	s_cselect_b32 s63, s18, s13
	s_cselect_b32 s62, s19, s12
	s_cselect_b32 s61, s26, s55
	s_cselect_b32 s60, s47, s49
	s_add_i32 s85, 0, 0x14000
	v_add_u32_e32 v130, s84, v247
	v_add_u32_e32 v158, s85, v247
	ds_read_b128 v[114:117], v130
	ds_read_b128 v[118:121], v130 offset:1024
	ds_read_b128 v[126:129], v130 offset:2048
	ds_read_b128 v[130:133], v130 offset:3072
	ds_read_b128 v[138:141], v158
	ds_read_b128 v[142:145], v158 offset:1024
	ds_read_b128 v[146:149], v158 offset:2048
	ds_read_b128 v[158:161], v158 offset:3072
	v_lshl_add_u64 v[214:215], s[58:59], 0, v[212:213]
	s_add_i32 m0, s57, 0xc000
	ds_read_b128 v[162:165], v249
	ds_read_b128 v[166:169], v249 offset:1024
	ds_read_b128 v[170:173], v249 offset:2048
	ds_read_b128 v[174:177], v249 offset:3072
	ds_read_b128 v[178:181], v249 offset:4096
	ds_read_b128 v[182:185], v249 offset:5120
	ds_read_b128 v[186:189], v249 offset:6144
	ds_read_b128 v[190:193], v249 offset:7168
	global_load_lds_dwordx4 v[214:215], off
	v_lshl_add_u64 v[214:215], s[58:59], 0, v[210:211]
	s_add_i32 m0, s57, 0xe000
	s_nop 0
	global_load_lds_dwordx4 v[214:215], off
	s_waitcnt vmcnt(8)
	s_waitcnt lgkmcnt(0)
	s_barrier
	s_setprio 1
	s_waitcnt lgkmcnt(0)
	v_mfma_f32_16x16x32_bf16 v[154:157], v[114:117], v[162:165], v[154:157]
	v_mfma_f32_16x16x32_bf16 v[150:153], v[126:129], v[162:165], v[150:153]
	v_mfma_f32_16x16x32_bf16 v[110:113], v[114:117], v[170:173], v[110:113]
	v_mfma_f32_16x16x32_bf16 v[106:109], v[126:129], v[170:173], v[106:109]
	v_mfma_f32_16x16x32_bf16 v[92:95], v[114:117], v[178:181], v[92:95]
	v_mfma_f32_16x16x32_bf16 v[88:91], v[126:129], v[178:181], v[88:91]
	v_mfma_f32_16x16x32_bf16 v[76:79], v[114:117], v[186:189], v[76:79]
	v_mfma_f32_16x16x32_bf16 v[72:75], v[126:129], v[186:189], v[72:75]
	v_mfma_f32_16x16x32_bf16 v[154:157], v[118:121], v[166:169], v[154:157]
	v_mfma_f32_16x16x32_bf16 v[150:153], v[130:133], v[166:169], v[150:153]
	v_mfma_f32_16x16x32_bf16 v[110:113], v[118:121], v[174:177], v[110:113]
	v_mfma_f32_16x16x32_bf16 v[106:109], v[130:133], v[174:177], v[106:109]
	v_mfma_f32_16x16x32_bf16 v[92:95], v[118:121], v[182:185], v[92:95]
	v_mfma_f32_16x16x32_bf16 v[88:91], v[130:133], v[182:185], v[88:91]
	v_mfma_f32_16x16x32_bf16 v[76:79], v[118:121], v[190:193], v[76:79]
	v_mfma_f32_16x16x32_bf16 v[72:75], v[130:133], v[190:193], v[72:75]
	v_mfma_f32_16x16x32_bf16 v[134:137], v[138:141], v[162:165], v[134:137]
	v_mfma_f32_16x16x32_bf16 v[122:125], v[146:149], v[162:165], v[122:125]
	v_mfma_f32_16x16x32_bf16 v[102:105], v[138:141], v[170:173], v[102:105]
	v_mfma_f32_16x16x32_bf16 v[98:101], v[146:149], v[170:173], v[98:101]
	v_mfma_f32_16x16x32_bf16 v[84:87], v[138:141], v[178:181], v[84:87]
	v_mfma_f32_16x16x32_bf16 v[80:83], v[146:149], v[178:181], v[80:83]
	v_mfma_f32_16x16x32_bf16 v[68:71], v[138:141], v[186:189], v[68:71]
	v_mfma_f32_16x16x32_bf16 v[64:67], v[146:149], v[186:189], v[64:67]
	v_mfma_f32_16x16x32_bf16 v[134:137], v[142:145], v[166:169], v[134:137]
	v_mfma_f32_16x16x32_bf16 v[122:125], v[158:161], v[166:169], v[122:125]
	v_mfma_f32_16x16x32_bf16 v[102:105], v[142:145], v[174:177], v[102:105]
	v_mfma_f32_16x16x32_bf16 v[98:101], v[158:161], v[174:177], v[98:101]
	v_mfma_f32_16x16x32_bf16 v[84:87], v[142:145], v[182:185], v[84:87]
	v_mfma_f32_16x16x32_bf16 v[80:83], v[158:161], v[182:185], v[80:83]
	v_mfma_f32_16x16x32_bf16 v[68:71], v[142:145], v[190:193], v[68:71]
	v_mfma_f32_16x16x32_bf16 v[64:67], v[158:161], v[190:193], v[64:67]
	s_setprio 0
	s_barrier
	s_add_i32 s12, s84, s11
	v_lshl_add_u64 v[214:215], s[60:61], 0, v[204:205]
	s_mov_b32 m0, s12
	ds_read_b128 v[162:165], v249 offset:16384
	ds_read_b128 v[166:169], v249 offset:17408
	ds_read_b128 v[170:173], v249 offset:18432
	ds_read_b128 v[174:177], v249 offset:19456
	ds_read_b128 v[178:181], v249 offset:20480
	ds_read_b128 v[182:185], v249 offset:21504
	ds_read_b128 v[186:189], v249 offset:22528
	ds_read_b128 v[190:193], v249 offset:23552
	global_load_lds_dwordx4 v[214:215], off
	s_add_i32 m0, s12, 0x2000
	s_add_u32 s12, s60, 0x80000
	v_lshl_add_u64 v[216:217], s[60:61], 0, v[208:209]
	s_addc_u32 s13, s61, 0
	s_add_i32 s84, s85, s11
	global_load_lds_dwordx4 v[216:217], off
	v_lshl_add_u64 v[218:219], s[12:13], 0, v[204:205]
	s_mov_b32 m0, s84
	v_lshl_add_u64 v[220:221], s[62:63], 0, v[206:207]
	global_load_lds_dwordx4 v[218:219], off
	v_lshl_add_u64 v[218:219], s[12:13], 0, v[208:209]
	s_add_i32 m0, s84, 0x2000
	s_nop 0
	global_load_lds_dwordx4 v[218:219], off
	v_lshl_add_u64 v[218:219], s[62:63], 0, v[202:203]
	s_mov_b32 m0, s57
	s_nop 0
	global_load_lds_dwordx4 v[218:219], off
	s_mov_b32 m0, s65
	s_nop 0
	global_load_lds_dwordx4 v[220:221], off
	s_waitcnt vmcnt(8)
	s_waitcnt lgkmcnt(0)
	s_barrier
; #define PG8_STAGE(bufoff, gbase, voff) do { _Pragma("unroll") for (int _i = 0; _i < 2; ++_i) \
;         __builtin_amdgcn_global_load_lds((const unsigned*)((const char*)(gbase) + (voff)[_i]), (PG8_LAS unsigned*)(lds + (bufoff) + ldsw + _i * 8192), 16, 0, 0); } while (0)
; #define PG8_LDA(dst, b, h) do { _Pragma("unroll") for (int m = 0; m < 4; ++m) _Pragma("unroll") for (int k = 0; k < 2; ++k) dst[m][k] = *(const PG8_LAS bf16x8*)(lds + PG8_SA(b, h) + aoff + m * 2048 + k * 1024); } while (0)
; #define PG8_LDB(dst, b, h) do { _Pragma("unroll") for (int n = 0; n < 2; ++n) _Pragma("unroll") for (int k = 0; k < 2; ++k) dst[n][k] = *(const PG8_LAS bf16x8*)(lds + PG8_SB(b, h) + boff + n * 2048 + k * 1024); } while (0)
; #define PG8_MMA(ai, bj, At, Bt) do { __builtin_amdgcn_s_setprio(1); _Pragma("unroll") for (int m = 0; m < 4; ++m) _Pragma("unroll") for (int n = 0; n < 2; ++n) _Pragma("unroll") for (int k = 0; k < 2; ++k) \
;         acc[ai][bj][m][n] = __builtin_amdgcn_mfma_f32_16x16x32_bf16(Bt[n][k], At[m][k], acc[ai][bj][m][n], 0, 0, 0); __builtin_amdgcn_s_setprio(0); } while (0)
; #define PG8_WAIT_V(n) asm volatile("s_waitcnt vmcnt(" #n ")" ::: "memory")
; #define PG8_WAIT_L(n) asm volatile("s_waitcnt lgkmcnt(" #n ")" ::: "memory")
; #define PG8_BAR __builtin_amdgcn_s_barrier()
; #define PG8_SCHED __builtin_amdgcn_sched_barrier(0)
; template <class Epi, class Sched, bool ALIGN_EPI = false, bool SP2 = false>
; __device__ __forceinline__ void gemm_phase(PG8_LAS unsigned char* lds, const Gemm g, const Sched& S, const Epi& E) {
;     ...
;             PG8_WAIT_V(8); PG8_WAIT_L(0); PG8_BAR; PG8_MMA(1, 0, At, B0); PG8_MMA(1, 1, At, B1); PG8_BAR; PG8_SCHED;
;             PG8_LDB(B0, 1, 0); PG8_LDB(B1, 1, 1); PG8_SCHED; PG8_LDA(At, 1, 0); PG8_STAGE(PG8_SA(0, 1), a2 + hstep, voffA);
;             PG8_WAIT_V(8); PG8_WAIT_L(0); PG8_BAR; PG8_MMA(0, 0, At, B0); PG8_MMA(0, 1, At, B1); PG8_BAR; PG8_SCHED;
	s_setprio 1
	s_waitcnt lgkmcnt(0)
	v_mfma_f32_16x16x32_bf16 v[60:63], v[114:117], v[162:165], v[60:63]
	v_mfma_f32_16x16x32_bf16 v[56:59], v[126:129], v[162:165], v[56:59]
	v_mfma_f32_16x16x32_bf16 v[44:47], v[114:117], v[170:173], v[44:47]
	v_mfma_f32_16x16x32_bf16 v[40:43], v[126:129], v[170:173], v[40:43]
	v_mfma_f32_16x16x32_bf16 v[28:31], v[114:117], v[178:181], v[28:31]
	v_mfma_f32_16x16x32_bf16 v[24:27], v[126:129], v[178:181], v[24:27]
	v_mfma_f32_16x16x32_bf16 v[12:15], v[114:117], v[186:189], v[12:15]
	v_mfma_f32_16x16x32_bf16 v[8:11], v[126:129], v[186:189], v[8:11]
	v_mfma_f32_16x16x32_bf16 v[60:63], v[118:121], v[166:169], v[60:63]
	v_mfma_f32_16x16x32_bf16 v[56:59], v[130:133], v[166:169], v[56:59]
	v_mfma_f32_16x16x32_bf16 v[44:47], v[118:121], v[174:177], v[44:47]
	v_mfma_f32_16x16x32_bf16 v[40:43], v[130:133], v[174:177], v[40:43]
	v_mfma_f32_16x16x32_bf16 v[28:31], v[118:121], v[182:185], v[28:31]
	v_mfma_f32_16x16x32_bf16 v[24:27], v[130:133], v[182:185], v[24:27]
	v_mfma_f32_16x16x32_bf16 v[12:15], v[118:121], v[190:193], v[12:15]
	v_mfma_f32_16x16x32_bf16 v[8:11], v[130:133], v[190:193], v[8:11]
	v_mfma_f32_16x16x32_bf16 v[52:55], v[138:141], v[162:165], v[52:55]
	v_mfma_f32_16x16x32_bf16 v[48:51], v[146:149], v[162:165], v[48:51]
	v_mfma_f32_16x16x32_bf16 v[36:39], v[138:141], v[170:173], v[36:39]
	v_mfma_f32_16x16x32_bf16 v[32:35], v[146:149], v[170:173], v[32:35]
	v_mfma_f32_16x16x32_bf16 v[20:23], v[138:141], v[178:181], v[20:23]
	v_mfma_f32_16x16x32_bf16 v[16:19], v[146:149], v[178:181], v[16:19]
	v_mfma_f32_16x16x32_bf16 v[4:7], v[138:141], v[186:189], v[4:7]
	v_mfma_f32_16x16x32_bf16 v[0:3], v[146:149], v[186:189], v[0:3]
	v_mfma_f32_16x16x32_bf16 v[52:55], v[142:145], v[166:169], v[52:55]
	v_mfma_f32_16x16x32_bf16 v[48:51], v[158:161], v[166:169], v[48:51]
	v_mfma_f32_16x16x32_bf16 v[36:39], v[142:145], v[174:177], v[36:39]
	v_mfma_f32_16x16x32_bf16 v[32:35], v[158:161], v[174:177], v[32:35]
	v_mfma_f32_16x16x32_bf16 v[20:23], v[142:145], v[182:185], v[20:23]
	v_mfma_f32_16x16x32_bf16 v[16:19], v[158:161], v[182:185], v[16:19]
	v_mfma_f32_16x16x32_bf16 v[4:7], v[142:145], v[190:193], v[4:7]
	v_mfma_f32_16x16x32_bf16 v[0:3], v[158:161], v[190:193], v[0:3]
	s_setprio 0
	s_barrier
	s_add_i32 s84, 0, 0x18000
	s_add_i32 s85, 0, 0x1c000
	v_add_u32_e32 v130, s84, v247
	v_add_u32_e32 v158, s85, v247
	ds_read_b128 v[114:117], v130
	ds_read_b128 v[118:121], v130 offset:1024
	ds_read_b128 v[126:129], v130 offset:2048
	ds_read_b128 v[130:133], v130 offset:3072
	ds_read_b128 v[138:141], v158
	ds_read_b128 v[142:145], v158 offset:1024
	ds_read_b128 v[146:149], v158 offset:2048
	ds_read_b128 v[158:161], v158 offset:3072
	s_add_u32 s12, s62, 0x80000
	s_addc_u32 s13, s63, 0
	s_mov_b32 m0, s66
	v_lshl_add_u64 v[222:223], s[12:13], 0, v[202:203]
	ds_read_b128 v[162:165], v249 offset:32768
	ds_read_b128 v[166:169], v249 offset:33792
	ds_read_b128 v[170:173], v249 offset:34816
	ds_read_b128 v[174:177], v249 offset:35840
	ds_read_b128 v[178:181], v249 offset:36864
	ds_read_b128 v[182:185], v249 offset:37888
	ds_read_b128 v[186:189], v249 offset:38912
	ds_read_b128 v[190:193], v249 offset:39936
	global_load_lds_dwordx4 v[222:223], off
	v_lshl_add_u64 v[222:223], s[12:13], 0, v[206:207]
	s_mov_b32 m0, s67
	s_nop 0
	global_load_lds_dwordx4 v[222:223], off
	s_waitcnt vmcnt(8)
	s_waitcnt lgkmcnt(0)
	s_barrier
	s_setprio 1
	s_waitcnt lgkmcnt(0)
	v_mfma_f32_16x16x32_bf16 v[154:157], v[114:117], v[162:165], v[154:157]
	v_mfma_f32_16x16x32_bf16 v[150:153], v[126:129], v[162:165], v[150:153]
	v_mfma_f32_16x16x32_bf16 v[110:113], v[114:117], v[170:173], v[110:113]
	v_mfma_f32_16x16x32_bf16 v[106:109], v[126:129], v[170:173], v[106:109]
	v_mfma_f32_16x16x32_bf16 v[92:95], v[114:117], v[178:181], v[92:95]
	v_mfma_f32_16x16x32_bf16 v[88:91], v[126:129], v[178:181], v[88:91]
	v_mfma_f32_16x16x32_bf16 v[76:79], v[114:117], v[186:189], v[76:79]
	v_mfma_f32_16x16x32_bf16 v[72:75], v[126:129], v[186:189], v[72:75]
	v_mfma_f32_16x16x32_bf16 v[154:157], v[118:121], v[166:169], v[154:157]
	v_mfma_f32_16x16x32_bf16 v[150:153], v[130:133], v[166:169], v[150:153]
	v_mfma_f32_16x16x32_bf16 v[110:113], v[118:121], v[174:177], v[110:113]
	v_mfma_f32_16x16x32_bf16 v[106:109], v[130:133], v[174:177], v[106:109]
	v_mfma_f32_16x16x32_bf16 v[92:95], v[118:121], v[182:185], v[92:95]
	v_mfma_f32_16x16x32_bf16 v[88:91], v[130:133], v[182:185], v[88:91]
	v_mfma_f32_16x16x32_bf16 v[76:79], v[118:121], v[190:193], v[76:79]
	v_mfma_f32_16x16x32_bf16 v[72:75], v[130:133], v[190:193], v[72:75]
	v_mfma_f32_16x16x32_bf16 v[134:137], v[138:141], v[162:165], v[134:137]
	v_mfma_f32_16x16x32_bf16 v[122:125], v[146:149], v[162:165], v[122:125]
	v_mfma_f32_16x16x32_bf16 v[102:105], v[138:141], v[170:173], v[102:105]
	v_mfma_f32_16x16x32_bf16 v[98:101], v[146:149], v[170:173], v[98:101]
	v_mfma_f32_16x16x32_bf16 v[84:87], v[138:141], v[178:181], v[84:87]
	v_mfma_f32_16x16x32_bf16 v[80:83], v[146:149], v[178:181], v[80:83]
	v_mfma_f32_16x16x32_bf16 v[68:71], v[138:141], v[186:189], v[68:71]
	v_mfma_f32_16x16x32_bf16 v[64:67], v[146:149], v[186:189], v[64:67]
	v_mfma_f32_16x16x32_bf16 v[134:137], v[142:145], v[166:169], v[134:137]
	v_mfma_f32_16x16x32_bf16 v[122:125], v[158:161], v[166:169], v[122:125]
	v_mfma_f32_16x16x32_bf16 v[102:105], v[142:145], v[174:177], v[102:105]
	v_mfma_f32_16x16x32_bf16 v[98:101], v[158:161], v[174:177], v[98:101]
	v_mfma_f32_16x16x32_bf16 v[84:87], v[142:145], v[182:185], v[84:87]
	v_mfma_f32_16x16x32_bf16 v[80:83], v[158:161], v[182:185], v[80:83]
	v_mfma_f32_16x16x32_bf16 v[68:71], v[142:145], v[190:193], v[68:71]
	v_mfma_f32_16x16x32_bf16 v[64:67], v[158:161], v[190:193], v[64:67]
	s_setprio 0
	s_barrier
; #define PG8_STAGE(bufoff, gbase, voff) do { _Pragma("unroll") for (int _i = 0; _i < 2; ++_i) \
;         __builtin_amdgcn_global_load_lds((const unsigned*)((const char*)(gbase) + (voff)[_i]), (PG8_LAS unsigned*)(lds + (bufoff) + ldsw + _i * 8192), 16, 0, 0); } while (0)
; #define PG8_LDA(dst, b, h) do { _Pragma("unroll") for (int m = 0; m < 4; ++m) _Pragma("unroll") for (int k = 0; k < 2; ++k) dst[m][k] = *(const PG8_LAS bf16x8*)(lds + PG8_SA(b, h) + aoff + m * 2048 + k * 1024); } while (0)
; #define PG8_MMA(ai, bj, At, Bt) do { __builtin_amdgcn_s_setprio(1); _Pragma("unroll") for (int m = 0; m < 4; ++m) _Pragma("unroll") for (int n = 0; n < 2; ++n) _Pragma("unroll") for (int k = 0; k < 2; ++k) \
;         acc[ai][bj][m][n] = __builtin_amdgcn_mfma_f32_16x16x32_bf16(Bt[n][k], At[m][k], acc[ai][bj][m][n], 0, 0, 0); __builtin_amdgcn_s_setprio(0); } while (0)
; #define PG8_WAIT_V(n) asm volatile("s_waitcnt vmcnt(" #n ")" ::: "memory")
; #define PG8_WAIT_L(n) asm volatile("s_waitcnt lgkmcnt(" #n ")" ::: "memory")
; #define PG8_BAR __builtin_amdgcn_s_barrier()
; #define PG8_SCHED __builtin_amdgcn_sched_barrier(0)
; template <class Epi, class Sched, bool ALIGN_EPI = false, bool SP2 = false>
; __device__ __forceinline__ void gemm_phase(PG8_LAS unsigned char* lds, const Gemm g, const Sched& S, const Epi& E) {
;     ...
;         for (int t = 0; t < nt; t += 2) {
;             const bool last = (t == nt - 2);
;     ...
;             PG8_LDA(At, 1, 1); PG8_STAGE(PG8_SB(1, 0), b3, voffB); PG8_STAGE(PG8_SB(1, 1), b3 + hstep, voffB); PG8_STAGE(PG8_SA(1, 0), a3, voffA);
;             PG8_WAIT_V(8); PG8_WAIT_L(0); PG8_BAR; PG8_MMA(1, 0, At, B0); PG8_MMA(1, 1, At, B1); PG8_BAR; PG8_SCHED;
	s_add_i32 s12, s84, s11
	v_lshl_add_u64 v[214:215], v[214:215], 0, s[36:37]
	s_mov_b32 m0, s12
	ds_read_b128 v[162:165], v249 offset:49152
	ds_read_b128 v[166:169], v249 offset:50176
	ds_read_b128 v[170:173], v249 offset:51200
	ds_read_b128 v[174:177], v249 offset:52224
	ds_read_b128 v[178:181], v249 offset:53248
	ds_read_b128 v[182:185], v249 offset:54272
	ds_read_b128 v[186:189], v249 offset:55296
	ds_read_b128 v[190:193], v249 offset:56320
	global_load_lds_dwordx4 v[214:215], off
	s_add_i32 m0, s12, 0x2000
	s_add_u32 s12, s60, 0x80080
	v_lshl_add_u64 v[214:215], v[216:217], 0, s[36:37]
	s_addc_u32 s13, s61, 0
	s_add_i32 s60, s85, s11
	global_load_lds_dwordx4 v[214:215], off
	v_lshl_add_u64 v[214:215], s[12:13], 0, v[204:205]
	s_mov_b32 m0, s60
	s_nop 0
	global_load_lds_dwordx4 v[214:215], off
	v_lshl_add_u64 v[214:215], s[12:13], 0, v[208:209]
	s_add_i32 m0, s60, 0x2000
	s_nop 0
	global_load_lds_dwordx4 v[214:215], off
	v_lshl_add_u64 v[214:215], v[218:219], 0, s[36:37]
	s_mov_b32 m0, s69
	s_nop 0
	global_load_lds_dwordx4 v[214:215], off
	v_lshl_add_u64 v[214:215], v[220:221], 0, s[36:37]
	s_mov_b32 m0, s70
	s_nop 0
	global_load_lds_dwordx4 v[214:215], off
	s_waitcnt vmcnt(8)
	s_waitcnt lgkmcnt(0)
	s_barrier
	s_setprio 1
	s_waitcnt lgkmcnt(0)
	v_mfma_f32_16x16x32_bf16 v[60:63], v[114:117], v[162:165], v[60:63]
	v_mfma_f32_16x16x32_bf16 v[56:59], v[126:129], v[162:165], v[56:59]
	v_mfma_f32_16x16x32_bf16 v[44:47], v[114:117], v[170:173], v[44:47]
	v_mfma_f32_16x16x32_bf16 v[40:43], v[126:129], v[170:173], v[40:43]
	v_mfma_f32_16x16x32_bf16 v[28:31], v[114:117], v[178:181], v[28:31]
	v_mfma_f32_16x16x32_bf16 v[24:27], v[126:129], v[178:181], v[24:27]
	v_mfma_f32_16x16x32_bf16 v[12:15], v[114:117], v[186:189], v[12:15]
	v_mfma_f32_16x16x32_bf16 v[8:11], v[126:129], v[186:189], v[8:11]
	v_mfma_f32_16x16x32_bf16 v[60:63], v[118:121], v[166:169], v[60:63]
	v_mfma_f32_16x16x32_bf16 v[56:59], v[130:133], v[166:169], v[56:59]
	v_mfma_f32_16x16x32_bf16 v[44:47], v[118:121], v[174:177], v[44:47]
	v_mfma_f32_16x16x32_bf16 v[40:43], v[130:133], v[174:177], v[40:43]
	v_mfma_f32_16x16x32_bf16 v[28:31], v[118:121], v[182:185], v[28:31]
	v_mfma_f32_16x16x32_bf16 v[24:27], v[130:133], v[182:185], v[24:27]
	v_mfma_f32_16x16x32_bf16 v[12:15], v[118:121], v[190:193], v[12:15]
	v_mfma_f32_16x16x32_bf16 v[8:11], v[130:133], v[190:193], v[8:11]
	v_mfma_f32_16x16x32_bf16 v[52:55], v[138:141], v[162:165], v[52:55]
	v_mfma_f32_16x16x32_bf16 v[48:51], v[146:149], v[162:165], v[48:51]
	v_mfma_f32_16x16x32_bf16 v[36:39], v[138:141], v[170:173], v[36:39]
	v_mfma_f32_16x16x32_bf16 v[32:35], v[146:149], v[170:173], v[32:35]
	v_mfma_f32_16x16x32_bf16 v[20:23], v[138:141], v[178:181], v[20:23]
	v_mfma_f32_16x16x32_bf16 v[16:19], v[146:149], v[178:181], v[16:19]
	v_mfma_f32_16x16x32_bf16 v[4:7], v[138:141], v[186:189], v[4:7]
	v_mfma_f32_16x16x32_bf16 v[0:3], v[146:149], v[186:189], v[0:3]
	v_mfma_f32_16x16x32_bf16 v[52:55], v[142:145], v[166:169], v[52:55]
	v_mfma_f32_16x16x32_bf16 v[48:51], v[158:161], v[166:169], v[48:51]
	v_mfma_f32_16x16x32_bf16 v[36:39], v[142:145], v[174:177], v[36:39]
	v_mfma_f32_16x16x32_bf16 v[32:35], v[158:161], v[174:177], v[32:35]
	v_mfma_f32_16x16x32_bf16 v[20:23], v[142:145], v[182:185], v[20:23]
	v_mfma_f32_16x16x32_bf16 v[16:19], v[158:161], v[182:185], v[16:19]
	v_mfma_f32_16x16x32_bf16 v[4:7], v[142:145], v[190:193], v[4:7]
	v_mfma_f32_16x16x32_bf16 v[0:3], v[158:161], v[190:193], v[0:3]
	s_setprio 0
	s_barrier
	s_add_i32 s73, s73, 2
	s_add_u32 s49, s49, 0x100
	s_addc_u32 s55, s55, 0
	s_add_u32 s58, s58, 0x100
	s_addc_u32 s59, s59, 0
	s_cmp_gt_u32 s73, 29
	s_cbranch_scc0 .LBB0_892
	s_and_b64 vcc, exec, s[14:15]
	s_cbranch_vccz .LBB0_895
	s_barrier

; #define PG8_STAGE(bufoff, gbase, voff) do { _Pragma("unroll") for (int _i = 0; _i < 2; ++_i) \
;         __builtin_amdgcn_global_load_lds((const unsigned*)((const char*)(gbase) + (voff)[_i]), (PG8_LAS unsigned*)(lds + (bufoff) + ldsw + _i * 8192), 16, 0, 0); } while (0)
; #define PG8_LDA(dst, b, h) do { _Pragma("unroll") for (int m = 0; m < 4; ++m) _Pragma("unroll") for (int k = 0; k < 2; ++k) dst[m][k] = *(const PG8_LAS bf16x8*)(lds + PG8_SA(b, h) + aoff + m * 2048 + k * 1024); } while (0)
; #define PG8_LDB(dst, b, h) do { _Pragma("unroll") for (int n = 0; n < 2; ++n) _Pragma("unroll") for (int k = 0; k < 2; ++k) dst[n][k] = *(const PG8_LAS bf16x8*)(lds + PG8_SB(b, h) + boff + n * 2048 + k * 1024); } while (0)
; #define PG8_MMA(ai, bj, At, Bt) do { __builtin_amdgcn_s_setprio(1); _Pragma("unroll") for (int m = 0; m < 4; ++m) _Pragma("unroll") for (int n = 0; n < 2; ++n) _Pragma("unroll") for (int k = 0; k < 2; ++k) \
;         acc[ai][bj][m][n] = __builtin_amdgcn_mfma_f32_16x16x32_bf16(Bt[n][k], At[m][k], acc[ai][bj][m][n], 0, 0, 0); __builtin_amdgcn_s_setprio(0); } while (0)
; #define PG8_WAIT_V(n) asm volatile("s_waitcnt vmcnt(" #n ")" ::: "memory")
; #define PG8_WAIT_L(n) asm volatile("s_waitcnt lgkmcnt(" #n ")" ::: "memory")
; template <class Epi, class Sched, bool ALIGN_EPI = false, bool SP2 = false>
; __device__ __forceinline__ void gemm_phase(PG8_LAS unsigned char* lds, const Gemm g, const Sched& S, const Epi& E) {
;     ...
;             const bool last = (t == nt - 2);
;             const char* a1 = cA + (size_t)(t + 1) * kstep;
;             const char* a2 = last ? nA : cA + (size_t)(t + 2) * kstep; const char* b2 = last ? nB : cB + (size_t)(t + 2) * kstep;
;             const char* a3 = a2 + kstep; const char* b3 = b2 + kstep;
;             if (last && has_next) S.a_ready(nxt);
;             if constexpr (SP2) {
;             PG8_LDB(B0, 0, 0); PG8_LDB(B1, 0, 1); PG8_SCHED; PG8_LDA(At, 0, 0); PG8_STAGE(PG8_SA(1, 1), a1 + hstep, voffA);
;             PG8_WAIT_V(8); PG8_WAIT_L(0); PG8_BAR; PG8_MMA(0, 0, At, B0); PG8_MMA(0, 1, At, B1); PG8_BAR; PG8_SCHED;
;             PG8_LDA(At, 0, 1); PG8_STAGE(PG8_SB(0, 0), b2, voffB); PG8_STAGE(PG8_SB(0, 1), b2 + hstep, voffB); PG8_STAGE(PG8_SA(0, 0), a2, voffA);
;             PG8_WAIT_V(8); PG8_WAIT_L(0); PG8_BAR; PG8_MMA(1, 0, At, B0); PG8_MMA(1, 1, At, B1); PG8_BAR; PG8_SCHED;
.LBB0_1016:
	s_add_u32 s12, s14, 0xfff80080
	s_addc_u32 s13, s15, -1
	s_add_i32 s70, 0, 0x10000
	s_cmp_eq_u32 s69, 28
	s_cselect_b32 s59, s1, s13
	s_cselect_b32 s58, s5, s12
	v_add_u32_e32 v148, s70, v149
	s_cselect_b32 s43, s10, s53
	s_cselect_b32 s42, s11, s51
	s_add_i32 s71, 0, 0x14000
	ds_read_b128 v[144:147], v148
	ds_read_b128 v[154:157], v148 offset:1024
	ds_read_b128 v[158:161], v148 offset:2048
	ds_read_b128 v[162:165], v148 offset:3072
	v_add_u32_e32 v148, s71, v149
	ds_read_b128 v[166:169], v148
	ds_read_b128 v[170:173], v148 offset:1024
	ds_read_b128 v[174:177], v148 offset:2048
	ds_read_b128 v[178:181], v148 offset:3072
	v_lshl_add_u64 v[222:223], s[14:15], 0, v[142:143]
	s_add_i32 m0, s61, 0xc000
	ds_read_b128 v[182:185], v152
	ds_read_b128 v[186:189], v152 offset:1024
	ds_read_b128 v[190:193], v152 offset:2048
	ds_read_b128 v[202:205], v152 offset:3072
	ds_read_b128 v[206:209], v152 offset:4096
	ds_read_b128 v[210:213], v152 offset:5120
	ds_read_b128 v[214:217], v152 offset:6144
	ds_read_b128 v[218:221], v152 offset:7168
	global_load_lds_dwordx4 v[222:223], off
	v_lshl_add_u64 v[222:223], s[14:15], 0, v[140:141]
	s_add_i32 m0, s61, 0xe000
	s_nop 0
	global_load_lds_dwordx4 v[222:223], off
	s_waitcnt vmcnt(8)
	s_waitcnt lgkmcnt(0)
	s_barrier
	s_setprio 1
	s_waitcnt lgkmcnt(0)
	v_mfma_f32_16x16x32_bf16 v[126:129], v[144:147], v[182:185], v[126:129]
	v_mfma_f32_16x16x32_bf16 v[122:125], v[158:161], v[182:185], v[122:125]
	v_mfma_f32_16x16x32_bf16 v[110:113], v[144:147], v[190:193], v[110:113]
	v_mfma_f32_16x16x32_bf16 v[106:109], v[158:161], v[190:193], v[106:109]
	v_mfma_f32_16x16x32_bf16 v[92:95], v[144:147], v[206:209], v[92:95]
	v_mfma_f32_16x16x32_bf16 v[88:91], v[158:161], v[206:209], v[88:91]
	v_mfma_f32_16x16x32_bf16 v[76:79], v[144:147], v[214:217], v[76:79]
	v_mfma_f32_16x16x32_bf16 v[72:75], v[158:161], v[214:217], v[72:75]
	v_mfma_f32_16x16x32_bf16 v[126:129], v[154:157], v[186:189], v[126:129]
	v_mfma_f32_16x16x32_bf16 v[122:125], v[162:165], v[186:189], v[122:125]
	v_mfma_f32_16x16x32_bf16 v[110:113], v[154:157], v[202:205], v[110:113]
	v_mfma_f32_16x16x32_bf16 v[106:109], v[162:165], v[202:205], v[106:109]
	v_mfma_f32_16x16x32_bf16 v[92:95], v[154:157], v[210:213], v[92:95]
	v_mfma_f32_16x16x32_bf16 v[88:91], v[162:165], v[210:213], v[88:91]
	v_mfma_f32_16x16x32_bf16 v[76:79], v[154:157], v[218:221], v[76:79]
	v_mfma_f32_16x16x32_bf16 v[72:75], v[162:165], v[218:221], v[72:75]
	v_mfma_f32_16x16x32_bf16 v[118:121], v[166:169], v[182:185], v[118:121]
	v_mfma_f32_16x16x32_bf16 v[114:117], v[174:177], v[182:185], v[114:117]
	v_mfma_f32_16x16x32_bf16 v[102:105], v[166:169], v[190:193], v[102:105]
	v_mfma_f32_16x16x32_bf16 v[98:101], v[174:177], v[190:193], v[98:101]
	v_mfma_f32_16x16x32_bf16 v[84:87], v[166:169], v[206:209], v[84:87]
	v_mfma_f32_16x16x32_bf16 v[80:83], v[174:177], v[206:209], v[80:83]
	v_mfma_f32_16x16x32_bf16 v[68:71], v[166:169], v[214:217], v[68:71]
	v_mfma_f32_16x16x32_bf16 v[64:67], v[174:177], v[214:217], v[64:67]
	v_mfma_f32_16x16x32_bf16 v[118:121], v[170:173], v[186:189], v[118:121]
	v_mfma_f32_16x16x32_bf16 v[114:117], v[178:181], v[186:189], v[114:117]
	v_mfma_f32_16x16x32_bf16 v[102:105], v[170:173], v[202:205], v[102:105]
	v_mfma_f32_16x16x32_bf16 v[98:101], v[178:181], v[202:205], v[98:101]
	v_mfma_f32_16x16x32_bf16 v[84:87], v[170:173], v[210:213], v[84:87]
	v_mfma_f32_16x16x32_bf16 v[80:83], v[178:181], v[210:213], v[80:83]
	v_mfma_f32_16x16x32_bf16 v[68:71], v[170:173], v[218:221], v[68:71]
	v_mfma_f32_16x16x32_bf16 v[64:67], v[178:181], v[218:221], v[64:67]
	s_setprio 0
	s_barrier
	s_add_i32 s12, s70, s9
	v_lshl_add_u64 v[222:223], s[42:43], 0, v[132:133]
	s_mov_b32 m0, s12
	ds_read_b128 v[182:185], v152 offset:16384
	ds_read_b128 v[186:189], v152 offset:17408
	ds_read_b128 v[190:193], v152 offset:18432
	ds_read_b128 v[202:205], v152 offset:19456
	ds_read_b128 v[206:209], v152 offset:20480
	ds_read_b128 v[210:213], v152 offset:21504
	ds_read_b128 v[214:217], v152 offset:22528
	ds_read_b128 v[218:221], v152 offset:23552
	global_load_lds_dwordx4 v[222:223], off
	s_add_i32 m0, s12, 0x2000
	s_add_u32 s12, s42, 0x80000
	v_lshl_add_u64 v[224:225], s[42:43], 0, v[136:137]
	s_addc_u32 s13, s43, 0
	s_add_i32 s70, s71, s9
	global_load_lds_dwordx4 v[224:225], off
	v_lshl_add_u64 v[226:227], s[12:13], 0, v[132:133]
	s_mov_b32 m0, s70
	v_lshl_add_u64 v[228:229], s[58:59], 0, v[134:135]
	global_load_lds_dwordx4 v[226:227], off
	v_lshl_add_u64 v[226:227], s[12:13], 0, v[136:137]
	s_add_i32 m0, s70, 0x2000
	s_nop 0
	global_load_lds_dwordx4 v[226:227], off
	v_lshl_add_u64 v[226:227], s[58:59], 0, v[130:131]
	s_mov_b32 m0, s61
	s_nop 0
	global_load_lds_dwordx4 v[226:227], off
	s_mov_b32 m0, s62
	s_nop 0
	global_load_lds_dwordx4 v[228:229], off
	s_waitcnt vmcnt(8)
	s_waitcnt lgkmcnt(0)
	s_barrier
; #define PG8_STAGE(bufoff, gbase, voff) do { _Pragma("unroll") for (int _i = 0; _i < 2; ++_i) \
;         __builtin_amdgcn_global_load_lds((const unsigned*)((const char*)(gbase) + (voff)[_i]), (PG8_LAS unsigned*)(lds + (bufoff) + ldsw + _i * 8192), 16, 0, 0); } while (0)
; #define PG8_LDA(dst, b, h) do { _Pragma("unroll") for (int m = 0; m < 4; ++m) _Pragma("unroll") for (int k = 0; k < 2; ++k) dst[m][k] = *(const PG8_LAS bf16x8*)(lds + PG8_SA(b, h) + aoff + m * 2048 + k * 1024); } while (0)
; #define PG8_LDB(dst, b, h) do { _Pragma("unroll") for (int n = 0; n < 2; ++n) _Pragma("unroll") for (int k = 0; k < 2; ++k) dst[n][k] = *(const PG8_LAS bf16x8*)(lds + PG8_SB(b, h) + boff + n * 2048 + k * 1024); } while (0)
; #define PG8_MMA(ai, bj, At, Bt) do { __builtin_amdgcn_s_setprio(1); _Pragma("unroll") for (int m = 0; m < 4; ++m) _Pragma("unroll") for (int n = 0; n < 2; ++n) _Pragma("unroll") for (int k = 0; k < 2; ++k) \
;         acc[ai][bj][m][n] = __builtin_amdgcn_mfma_f32_16x16x32_bf16(Bt[n][k], At[m][k], acc[ai][bj][m][n], 0, 0, 0); __builtin_amdgcn_s_setprio(0); } while (0)
; #define PG8_WAIT_V(n) asm volatile("s_waitcnt vmcnt(" #n ")" ::: "memory")
; #define PG8_WAIT_L(n) asm volatile("s_waitcnt lgkmcnt(" #n ")" ::: "memory")
; #define PG8_BAR __builtin_amdgcn_s_barrier()
; #define PG8_SCHED __builtin_amdgcn_sched_barrier(0)
; template <class Epi, class Sched, bool ALIGN_EPI = false, bool SP2 = false>
; __device__ __forceinline__ void gemm_phase(PG8_LAS unsigned char* lds, const Gemm g, const Sched& S, const Epi& E) {
;     ...
;             PG8_WAIT_V(8); PG8_WAIT_L(0); PG8_BAR; PG8_MMA(1, 0, At, B0); PG8_MMA(1, 1, At, B1); PG8_BAR; PG8_SCHED;
;             PG8_LDB(B0, 1, 0); PG8_LDB(B1, 1, 1); PG8_SCHED; PG8_LDA(At, 1, 0); PG8_STAGE(PG8_SA(0, 1), a2 + hstep, voffA);
;             PG8_WAIT_V(8); PG8_WAIT_L(0); PG8_BAR; PG8_MMA(0, 0, At, B0); PG8_MMA(0, 1, At, B1); PG8_BAR; PG8_SCHED;
	s_setprio 1
	s_waitcnt lgkmcnt(0)
	v_mfma_f32_16x16x32_bf16 v[60:63], v[144:147], v[182:185], v[60:63]
	v_mfma_f32_16x16x32_bf16 v[56:59], v[158:161], v[182:185], v[56:59]
	v_mfma_f32_16x16x32_bf16 v[44:47], v[144:147], v[190:193], v[44:47]
	v_mfma_f32_16x16x32_bf16 v[40:43], v[158:161], v[190:193], v[40:43]
	v_mfma_f32_16x16x32_bf16 v[28:31], v[144:147], v[206:209], v[28:31]
	v_mfma_f32_16x16x32_bf16 v[24:27], v[158:161], v[206:209], v[24:27]
	v_mfma_f32_16x16x32_bf16 v[12:15], v[144:147], v[214:217], v[12:15]
	v_mfma_f32_16x16x32_bf16 v[8:11], v[158:161], v[214:217], v[8:11]
	v_mfma_f32_16x16x32_bf16 v[60:63], v[154:157], v[186:189], v[60:63]
	v_mfma_f32_16x16x32_bf16 v[56:59], v[162:165], v[186:189], v[56:59]
	v_mfma_f32_16x16x32_bf16 v[44:47], v[154:157], v[202:205], v[44:47]
	v_mfma_f32_16x16x32_bf16 v[40:43], v[162:165], v[202:205], v[40:43]
	v_mfma_f32_16x16x32_bf16 v[28:31], v[154:157], v[210:213], v[28:31]
	v_mfma_f32_16x16x32_bf16 v[24:27], v[162:165], v[210:213], v[24:27]
	v_mfma_f32_16x16x32_bf16 v[12:15], v[154:157], v[218:221], v[12:15]
	v_mfma_f32_16x16x32_bf16 v[8:11], v[162:165], v[218:221], v[8:11]
	v_mfma_f32_16x16x32_bf16 v[52:55], v[166:169], v[182:185], v[52:55]
	v_mfma_f32_16x16x32_bf16 v[48:51], v[174:177], v[182:185], v[48:51]
	v_mfma_f32_16x16x32_bf16 v[36:39], v[166:169], v[190:193], v[36:39]
	v_mfma_f32_16x16x32_bf16 v[32:35], v[174:177], v[190:193], v[32:35]
	v_mfma_f32_16x16x32_bf16 v[20:23], v[166:169], v[206:209], v[20:23]
	v_mfma_f32_16x16x32_bf16 v[16:19], v[174:177], v[206:209], v[16:19]
	v_mfma_f32_16x16x32_bf16 v[4:7], v[166:169], v[214:217], v[4:7]
	v_mfma_f32_16x16x32_bf16 v[0:3], v[174:177], v[214:217], v[0:3]
	v_mfma_f32_16x16x32_bf16 v[52:55], v[170:173], v[186:189], v[52:55]
	v_mfma_f32_16x16x32_bf16 v[48:51], v[178:181], v[186:189], v[48:51]
	v_mfma_f32_16x16x32_bf16 v[36:39], v[170:173], v[202:205], v[36:39]
	v_mfma_f32_16x16x32_bf16 v[32:35], v[178:181], v[202:205], v[32:35]
	v_mfma_f32_16x16x32_bf16 v[20:23], v[170:173], v[210:213], v[20:23]
	v_mfma_f32_16x16x32_bf16 v[16:19], v[178:181], v[210:213], v[16:19]
	v_mfma_f32_16x16x32_bf16 v[4:7], v[170:173], v[218:221], v[4:7]
	v_mfma_f32_16x16x32_bf16 v[0:3], v[178:181], v[218:221], v[0:3]
	s_setprio 0
	s_barrier
	s_add_i32 s70, 0, 0x18000
	v_add_u32_e32 v148, s70, v149
	s_add_i32 s71, 0, 0x1c000
	ds_read_b128 v[144:147], v148
	ds_read_b128 v[154:157], v148 offset:1024
	ds_read_b128 v[158:161], v148 offset:2048
	ds_read_b128 v[162:165], v148 offset:3072
	v_add_u32_e32 v148, s71, v149
	ds_read_b128 v[166:169], v148
	ds_read_b128 v[170:173], v148 offset:1024
	ds_read_b128 v[174:177], v148 offset:2048
	ds_read_b128 v[178:181], v148 offset:3072
	s_add_u32 s12, s58, 0x80000
	s_addc_u32 s13, s59, 0
	s_mov_b32 m0, s63
	v_lshl_add_u64 v[230:231], s[12:13], 0, v[130:131]
	ds_read_b128 v[182:185], v152 offset:32768
	ds_read_b128 v[186:189], v152 offset:33792
	ds_read_b128 v[190:193], v152 offset:34816
	ds_read_b128 v[202:205], v152 offset:35840
	ds_read_b128 v[206:209], v152 offset:36864
	ds_read_b128 v[210:213], v152 offset:37888
	ds_read_b128 v[214:217], v152 offset:38912
	ds_read_b128 v[218:221], v152 offset:39936
	global_load_lds_dwordx4 v[230:231], off
	v_lshl_add_u64 v[230:231], s[12:13], 0, v[134:135]
	s_mov_b32 m0, s65
	s_nop 0
	global_load_lds_dwordx4 v[230:231], off
	s_waitcnt vmcnt(8)
	s_waitcnt lgkmcnt(0)
	s_barrier
	s_setprio 1
	s_waitcnt lgkmcnt(0)
	v_mfma_f32_16x16x32_bf16 v[126:129], v[144:147], v[182:185], v[126:129]
	v_mfma_f32_16x16x32_bf16 v[122:125], v[158:161], v[182:185], v[122:125]
	v_mfma_f32_16x16x32_bf16 v[110:113], v[144:147], v[190:193], v[110:113]
	v_mfma_f32_16x16x32_bf16 v[106:109], v[158:161], v[190:193], v[106:109]
	v_mfma_f32_16x16x32_bf16 v[92:95], v[144:147], v[206:209], v[92:95]
	v_mfma_f32_16x16x32_bf16 v[88:91], v[158:161], v[206:209], v[88:91]
	v_mfma_f32_16x16x32_bf16 v[76:79], v[144:147], v[214:217], v[76:79]
	v_mfma_f32_16x16x32_bf16 v[72:75], v[158:161], v[214:217], v[72:75]
	v_mfma_f32_16x16x32_bf16 v[126:129], v[154:157], v[186:189], v[126:129]
	v_mfma_f32_16x16x32_bf16 v[122:125], v[162:165], v[186:189], v[122:125]
	v_mfma_f32_16x16x32_bf16 v[110:113], v[154:157], v[202:205], v[110:113]
	v_mfma_f32_16x16x32_bf16 v[106:109], v[162:165], v[202:205], v[106:109]
	v_mfma_f32_16x16x32_bf16 v[92:95], v[154:157], v[210:213], v[92:95]
	v_mfma_f32_16x16x32_bf16 v[88:91], v[162:165], v[210:213], v[88:91]
	v_mfma_f32_16x16x32_bf16 v[76:79], v[154:157], v[218:221], v[76:79]
	v_mfma_f32_16x16x32_bf16 v[72:75], v[162:165], v[218:221], v[72:75]
	v_mfma_f32_16x16x32_bf16 v[118:121], v[166:169], v[182:185], v[118:121]
	v_mfma_f32_16x16x32_bf16 v[114:117], v[174:177], v[182:185], v[114:117]
	v_mfma_f32_16x16x32_bf16 v[102:105], v[166:169], v[190:193], v[102:105]
	v_mfma_f32_16x16x32_bf16 v[98:101], v[174:177], v[190:193], v[98:101]
	v_mfma_f32_16x16x32_bf16 v[84:87], v[166:169], v[206:209], v[84:87]
	v_mfma_f32_16x16x32_bf16 v[80:83], v[174:177], v[206:209], v[80:83]
	v_mfma_f32_16x16x32_bf16 v[68:71], v[166:169], v[214:217], v[68:71]
	v_mfma_f32_16x16x32_bf16 v[64:67], v[174:177], v[214:217], v[64:67]
	v_mfma_f32_16x16x32_bf16 v[118:121], v[170:173], v[186:189], v[118:121]
	v_mfma_f32_16x16x32_bf16 v[114:117], v[178:181], v[186:189], v[114:117]
	v_mfma_f32_16x16x32_bf16 v[102:105], v[170:173], v[202:205], v[102:105]
	v_mfma_f32_16x16x32_bf16 v[98:101], v[178:181], v[202:205], v[98:101]
	v_mfma_f32_16x16x32_bf16 v[84:87], v[170:173], v[210:213], v[84:87]
	v_mfma_f32_16x16x32_bf16 v[80:83], v[178:181], v[210:213], v[80:83]
	v_mfma_f32_16x16x32_bf16 v[68:71], v[170:173], v[218:221], v[68:71]
	v_mfma_f32_16x16x32_bf16 v[64:67], v[178:181], v[218:221], v[64:67]
	s_setprio 0
	s_barrier
; #define PG8_STAGE(bufoff, gbase, voff) do { _Pragma("unroll") for (int _i = 0; _i < 2; ++_i) \
;         __builtin_amdgcn_global_load_lds((const unsigned*)((const char*)(gbase) + (voff)[_i]), (PG8_LAS unsigned*)(lds + (bufoff) + ldsw + _i * 8192), 16, 0, 0); } while (0)
; #define PG8_LDA(dst, b, h) do { _Pragma("unroll") for (int m = 0; m < 4; ++m) _Pragma("unroll") for (int k = 0; k < 2; ++k) dst[m][k] = *(const PG8_LAS bf16x8*)(lds + PG8_SA(b, h) + aoff + m * 2048 + k * 1024); } while (0)
; #define PG8_MMA(ai, bj, At, Bt) do { __builtin_amdgcn_s_setprio(1); _Pragma("unroll") for (int m = 0; m < 4; ++m) _Pragma("unroll") for (int n = 0; n < 2; ++n) _Pragma("unroll") for (int k = 0; k < 2; ++k) \
;         acc[ai][bj][m][n] = __builtin_amdgcn_mfma_f32_16x16x32_bf16(Bt[n][k], At[m][k], acc[ai][bj][m][n], 0, 0, 0); __builtin_amdgcn_s_setprio(0); } while (0)
; #define PG8_WAIT_V(n) asm volatile("s_waitcnt vmcnt(" #n ")" ::: "memory")
; #define PG8_WAIT_L(n) asm volatile("s_waitcnt lgkmcnt(" #n ")" ::: "memory")
; #define PG8_BAR __builtin_amdgcn_s_barrier()
; #define PG8_SCHED __builtin_amdgcn_sched_barrier(0)
; template <class Epi, class Sched, bool ALIGN_EPI = false, bool SP2 = false>
; __device__ __forceinline__ void gemm_phase(PG8_LAS unsigned char* lds, const Gemm g, const Sched& S, const Epi& E) {
;     ...
;         for (int t = 0; t < nt; t += 2) {
;             const bool last = (t == nt - 2);
;     ...
;             PG8_LDA(At, 1, 1); PG8_STAGE(PG8_SB(1, 0), b3, voffB); PG8_STAGE(PG8_SB(1, 1), b3 + hstep, voffB); PG8_STAGE(PG8_SA(1, 0), a3, voffA);
;             PG8_WAIT_V(8); PG8_WAIT_L(0); PG8_BAR; PG8_MMA(1, 0, At, B0); PG8_MMA(1, 1, At, B1); PG8_BAR; PG8_SCHED;
	s_add_i32 s12, s70, s9
	v_lshl_add_u64 v[222:223], v[222:223], 0, s[36:37]
	s_mov_b32 m0, s12
	ds_read_b128 v[182:185], v152 offset:49152
	ds_read_b128 v[186:189], v152 offset:50176
	ds_read_b128 v[190:193], v152 offset:51200
	ds_read_b128 v[202:205], v152 offset:52224
	ds_read_b128 v[206:209], v152 offset:53248
	ds_read_b128 v[210:213], v152 offset:54272
	ds_read_b128 v[214:217], v152 offset:55296
	ds_read_b128 v[218:221], v152 offset:56320
	global_load_lds_dwordx4 v[222:223], off
	s_add_i32 m0, s12, 0x2000
	s_add_u32 s12, s42, 0x80080
	v_lshl_add_u64 v[222:223], v[224:225], 0, s[36:37]
	s_addc_u32 s13, s43, 0
	s_add_i32 s42, s71, s9
	global_load_lds_dwordx4 v[222:223], off
	v_lshl_add_u64 v[222:223], s[12:13], 0, v[132:133]
	s_mov_b32 m0, s42
	s_nop 0
	global_load_lds_dwordx4 v[222:223], off
	v_lshl_add_u64 v[222:223], s[12:13], 0, v[136:137]
	s_add_i32 m0, s42, 0x2000
	s_nop 0
	global_load_lds_dwordx4 v[222:223], off
	v_lshl_add_u64 v[222:223], v[226:227], 0, s[36:37]
	s_mov_b32 m0, s66
	s_nop 0
	global_load_lds_dwordx4 v[222:223], off
	v_lshl_add_u64 v[222:223], v[228:229], 0, s[36:37]
	s_mov_b32 m0, s67
	s_nop 0
	global_load_lds_dwordx4 v[222:223], off
	s_waitcnt vmcnt(8)
	s_waitcnt lgkmcnt(0)
	s_barrier
	s_setprio 1
	s_waitcnt lgkmcnt(0)
	v_mfma_f32_16x16x32_bf16 v[60:63], v[144:147], v[182:185], v[60:63]
	v_mfma_f32_16x16x32_bf16 v[56:59], v[158:161], v[182:185], v[56:59]
	v_mfma_f32_16x16x32_bf16 v[44:47], v[144:147], v[190:193], v[44:47]
	v_mfma_f32_16x16x32_bf16 v[40:43], v[158:161], v[190:193], v[40:43]
	v_mfma_f32_16x16x32_bf16 v[28:31], v[144:147], v[206:209], v[28:31]
	v_mfma_f32_16x16x32_bf16 v[24:27], v[158:161], v[206:209], v[24:27]
	v_mfma_f32_16x16x32_bf16 v[12:15], v[144:147], v[214:217], v[12:15]
	v_mfma_f32_16x16x32_bf16 v[8:11], v[158:161], v[214:217], v[8:11]
	v_mfma_f32_16x16x32_bf16 v[60:63], v[154:157], v[186:189], v[60:63]
	v_mfma_f32_16x16x32_bf16 v[56:59], v[162:165], v[186:189], v[56:59]
	v_mfma_f32_16x16x32_bf16 v[44:47], v[154:157], v[202:205], v[44:47]
	v_mfma_f32_16x16x32_bf16 v[40:43], v[162:165], v[202:205], v[40:43]
	v_mfma_f32_16x16x32_bf16 v[28:31], v[154:157], v[210:213], v[28:31]
	v_mfma_f32_16x16x32_bf16 v[24:27], v[162:165], v[210:213], v[24:27]
	v_mfma_f32_16x16x32_bf16 v[12:15], v[154:157], v[218:221], v[12:15]
	v_mfma_f32_16x16x32_bf16 v[8:11], v[162:165], v[218:221], v[8:11]
	v_mfma_f32_16x16x32_bf16 v[52:55], v[166:169], v[182:185], v[52:55]
	v_mfma_f32_16x16x32_bf16 v[48:51], v[174:177], v[182:185], v[48:51]
	v_mfma_f32_16x16x32_bf16 v[36:39], v[166:169], v[190:193], v[36:39]
	v_mfma_f32_16x16x32_bf16 v[32:35], v[174:177], v[190:193], v[32:35]
	v_mfma_f32_16x16x32_bf16 v[20:23], v[166:169], v[206:209], v[20:23]
	v_mfma_f32_16x16x32_bf16 v[16:19], v[174:177], v[206:209], v[16:19]
	v_mfma_f32_16x16x32_bf16 v[4:7], v[166:169], v[214:217], v[4:7]
	v_mfma_f32_16x16x32_bf16 v[0:3], v[174:177], v[214:217], v[0:3]
	v_mfma_f32_16x16x32_bf16 v[52:55], v[170:173], v[186:189], v[52:55]
	v_mfma_f32_16x16x32_bf16 v[48:51], v[178:181], v[186:189], v[48:51]
	v_mfma_f32_16x16x32_bf16 v[36:39], v[170:173], v[202:205], v[36:39]
	v_mfma_f32_16x16x32_bf16 v[32:35], v[178:181], v[202:205], v[32:35]
	v_mfma_f32_16x16x32_bf16 v[20:23], v[170:173], v[210:213], v[20:23]
	v_mfma_f32_16x16x32_bf16 v[16:19], v[178:181], v[210:213], v[16:19]
	v_mfma_f32_16x16x32_bf16 v[4:7], v[170:173], v[218:221], v[4:7]
	v_mfma_f32_16x16x32_bf16 v[0:3], v[178:181], v[218:221], v[0:3]
	s_setprio 0
	s_barrier
	s_add_i32 s69, s69, 2
	s_add_u32 s51, s51, 0x100
	s_addc_u32 s53, s53, 0
	s_add_u32 s14, s14, 0x100
	s_addc_u32 s15, s15, 0
	s_cmp_gt_u32 s69, 29
	s_cbranch_scc0 .LBB0_1016
	s_and_b64 vcc, exec, s[48:49]
	s_cbranch_vccz .LBB0_1019
	s_barrier

; #define PG8_STAGE(bufoff, gbase, voff) do { _Pragma("unroll") for (int _i = 0; _i < 2; ++_i) \
;         __builtin_amdgcn_global_load_lds((const unsigned*)((const char*)(gbase) + (voff)[_i]), (PG8_LAS unsigned*)(lds + (bufoff) + ldsw + _i * 8192), 16, 0, 0); } while (0)
; #define PG8_LDA(dst, b, h) do { _Pragma("unroll") for (int m = 0; m < 4; ++m) _Pragma("unroll") for (int k = 0; k < 2; ++k) dst[m][k] = *(const PG8_LAS bf16x8*)(lds + PG8_SA(b, h) + aoff + m * 2048 + k * 1024); } while (0)
; #define PG8_LDB(dst, b, h) do { _Pragma("unroll") for (int n = 0; n < 2; ++n) _Pragma("unroll") for (int k = 0; k < 2; ++k) dst[n][k] = *(const PG8_LAS bf16x8*)(lds + PG8_SB(b, h) + boff + n * 2048 + k * 1024); } while (0)
; #define PG8_MMA(ai, bj, At, Bt) do { __builtin_amdgcn_s_setprio(1); _Pragma("unroll") for (int m = 0; m < 4; ++m) _Pragma("unroll") for (int n = 0; n < 2; ++n) _Pragma("unroll") for (int k = 0; k < 2; ++k) \
;         acc[ai][bj][m][n] = __builtin_amdgcn_mfma_f32_16x16x32_bf16(Bt[n][k], At[m][k], acc[ai][bj][m][n], 0, 0, 0); __builtin_amdgcn_s_setprio(0); } while (0)
; #define PG8_WAIT_V(n) asm volatile("s_waitcnt vmcnt(" #n ")" ::: "memory")
; #define PG8_WAIT_L(n) asm volatile("s_waitcnt lgkmcnt(" #n ")" ::: "memory")
; template <class Epi, class Sched, bool ALIGN_EPI = false, bool SP2 = false>
; __device__ __forceinline__ void gemm_phase(PG8_LAS unsigned char* lds, const Gemm g, const Sched& S, const Epi& E) {
;     ...
;             const bool last = (t == nt - 2);
;             const char* a1 = cA + (size_t)(t + 1) * kstep;
;             const char* a2 = last ? nA : cA + (size_t)(t + 2) * kstep; const char* b2 = last ? nB : cB + (size_t)(t + 2) * kstep;
;             const char* a3 = a2 + kstep; const char* b3 = b2 + kstep;
;             if (last && has_next) S.a_ready(nxt);
;             if constexpr (SP2) {
;             PG8_LDB(B0, 0, 0); PG8_LDB(B1, 0, 1); PG8_SCHED; PG8_LDA(At, 0, 0); PG8_STAGE(PG8_SA(1, 1), a1 + hstep, voffA);
;             PG8_WAIT_V(8); PG8_WAIT_L(0); PG8_BAR; PG8_MMA(0, 0, At, B0); PG8_MMA(0, 1, At, B1); PG8_BAR; PG8_SCHED;
;             PG8_LDA(At, 0, 1); PG8_STAGE(PG8_SB(0, 0), b2, voffB); PG8_STAGE(PG8_SB(0, 1), b2 + hstep, voffB); PG8_STAGE(PG8_SA(0, 0), a2, voffA);
;             PG8_WAIT_V(8); PG8_WAIT_L(0); PG8_BAR; PG8_MMA(1, 0, At, B0); PG8_MMA(1, 1, At, B1); PG8_BAR; PG8_SCHED;
.LBB0_1144:
	s_add_u32 s12, s58, 0xffe00080
	s_addc_u32 s13, s59, -1
	s_add_i32 s84, 0, 0x10000
	s_cmpk_eq_i32 s73, 0x7c
	s_cselect_b32 s63, s18, s13
	s_cselect_b32 s62, s19, s12
	s_cselect_b32 s61, s26, s55
	s_cselect_b32 s60, s47, s49
	s_add_i32 s85, 0, 0x14000
	v_add_u32_e32 v130, s84, v247
	v_add_u32_e32 v158, s85, v247
	ds_read_b128 v[114:117], v130
	ds_read_b128 v[118:121], v130 offset:1024
	ds_read_b128 v[126:129], v130 offset:2048
	ds_read_b128 v[130:133], v130 offset:3072
	ds_read_b128 v[138:141], v158
	ds_read_b128 v[142:145], v158 offset:1024
	ds_read_b128 v[146:149], v158 offset:2048
	ds_read_b128 v[158:161], v158 offset:3072
	v_lshl_add_u64 v[214:215], s[58:59], 0, v[212:213]
	s_add_i32 m0, s57, 0xc000
	ds_read_b128 v[162:165], v249
	ds_read_b128 v[166:169], v249 offset:1024
	ds_read_b128 v[170:173], v249 offset:2048
	ds_read_b128 v[174:177], v249 offset:3072
	ds_read_b128 v[178:181], v249 offset:4096
	ds_read_b128 v[182:185], v249 offset:5120
	ds_read_b128 v[186:189], v249 offset:6144
	ds_read_b128 v[190:193], v249 offset:7168
	global_load_lds_dwordx4 v[214:215], off
	v_lshl_add_u64 v[214:215], s[58:59], 0, v[210:211]
	s_add_i32 m0, s57, 0xe000
	s_nop 0
	global_load_lds_dwordx4 v[214:215], off
	s_waitcnt vmcnt(8)
	s_waitcnt lgkmcnt(0)
	s_barrier
	s_setprio 1
	s_waitcnt lgkmcnt(0)
	v_mfma_f32_16x16x32_bf16 v[154:157], v[114:117], v[162:165], v[154:157]
	v_mfma_f32_16x16x32_bf16 v[150:153], v[126:129], v[162:165], v[150:153]
	v_mfma_f32_16x16x32_bf16 v[110:113], v[114:117], v[170:173], v[110:113]
	v_mfma_f32_16x16x32_bf16 v[106:109], v[126:129], v[170:173], v[106:109]
	v_mfma_f32_16x16x32_bf16 v[92:95], v[114:117], v[178:181], v[92:95]
	v_mfma_f32_16x16x32_bf16 v[88:91], v[126:129], v[178:181], v[88:91]
	v_mfma_f32_16x16x32_bf16 v[76:79], v[114:117], v[186:189], v[76:79]
	v_mfma_f32_16x16x32_bf16 v[72:75], v[126:129], v[186:189], v[72:75]
	v_mfma_f32_16x16x32_bf16 v[154:157], v[118:121], v[166:169], v[154:157]
	v_mfma_f32_16x16x32_bf16 v[150:153], v[130:133], v[166:169], v[150:153]
	v_mfma_f32_16x16x32_bf16 v[110:113], v[118:121], v[174:177], v[110:113]
	v_mfma_f32_16x16x32_bf16 v[106:109], v[130:133], v[174:177], v[106:109]
	v_mfma_f32_16x16x32_bf16 v[92:95], v[118:121], v[182:185], v[92:95]
	v_mfma_f32_16x16x32_bf16 v[88:91], v[130:133], v[182:185], v[88:91]
	v_mfma_f32_16x16x32_bf16 v[76:79], v[118:121], v[190:193], v[76:79]
	v_mfma_f32_16x16x32_bf16 v[72:75], v[130:133], v[190:193], v[72:75]
	v_mfma_f32_16x16x32_bf16 v[134:137], v[138:141], v[162:165], v[134:137]
	v_mfma_f32_16x16x32_bf16 v[122:125], v[146:149], v[162:165], v[122:125]
	v_mfma_f32_16x16x32_bf16 v[102:105], v[138:141], v[170:173], v[102:105]
	v_mfma_f32_16x16x32_bf16 v[98:101], v[146:149], v[170:173], v[98:101]
	v_mfma_f32_16x16x32_bf16 v[84:87], v[138:141], v[178:181], v[84:87]
	v_mfma_f32_16x16x32_bf16 v[80:83], v[146:149], v[178:181], v[80:83]
	v_mfma_f32_16x16x32_bf16 v[68:71], v[138:141], v[186:189], v[68:71]
	v_mfma_f32_16x16x32_bf16 v[64:67], v[146:149], v[186:189], v[64:67]
	v_mfma_f32_16x16x32_bf16 v[134:137], v[142:145], v[166:169], v[134:137]
	v_mfma_f32_16x16x32_bf16 v[122:125], v[158:161], v[166:169], v[122:125]
	v_mfma_f32_16x16x32_bf16 v[102:105], v[142:145], v[174:177], v[102:105]
	v_mfma_f32_16x16x32_bf16 v[98:101], v[158:161], v[174:177], v[98:101]
	v_mfma_f32_16x16x32_bf16 v[84:87], v[142:145], v[182:185], v[84:87]
	v_mfma_f32_16x16x32_bf16 v[80:83], v[158:161], v[182:185], v[80:83]
	v_mfma_f32_16x16x32_bf16 v[68:71], v[142:145], v[190:193], v[68:71]
	v_mfma_f32_16x16x32_bf16 v[64:67], v[158:161], v[190:193], v[64:67]
	s_setprio 0
	s_barrier
	s_add_i32 s12, s84, s11
	v_lshl_add_u64 v[214:215], s[60:61], 0, v[204:205]
	s_mov_b32 m0, s12
	ds_read_b128 v[162:165], v249 offset:16384
	ds_read_b128 v[166:169], v249 offset:17408
	ds_read_b128 v[170:173], v249 offset:18432
	ds_read_b128 v[174:177], v249 offset:19456
	ds_read_b128 v[178:181], v249 offset:20480
	ds_read_b128 v[182:185], v249 offset:21504
	ds_read_b128 v[186:189], v249 offset:22528
	ds_read_b128 v[190:193], v249 offset:23552
	global_load_lds_dwordx4 v[214:215], off
	s_add_i32 m0, s12, 0x2000
	s_add_u32 s12, s60, 0x200000
	v_lshl_add_u64 v[216:217], s[60:61], 0, v[208:209]
	s_addc_u32 s13, s61, 0
	s_add_i32 s84, s85, s11
	global_load_lds_dwordx4 v[216:217], off
	v_lshl_add_u64 v[218:219], s[12:13], 0, v[204:205]
	s_mov_b32 m0, s84
	v_lshl_add_u64 v[220:221], s[62:63], 0, v[206:207]
	global_load_lds_dwordx4 v[218:219], off
	v_lshl_add_u64 v[218:219], s[12:13], 0, v[208:209]
	s_add_i32 m0, s84, 0x2000
	s_nop 0
	global_load_lds_dwordx4 v[218:219], off
	v_lshl_add_u64 v[218:219], s[62:63], 0, v[202:203]
	s_mov_b32 m0, s57
	s_nop 0
	global_load_lds_dwordx4 v[218:219], off
	s_mov_b32 m0, s65
	s_nop 0
	global_load_lds_dwordx4 v[220:221], off
	s_waitcnt vmcnt(8)
	s_waitcnt lgkmcnt(0)
	s_barrier
; #define PG8_STAGE(bufoff, gbase, voff) do { _Pragma("unroll") for (int _i = 0; _i < 2; ++_i) \
;         __builtin_amdgcn_global_load_lds((const unsigned*)((const char*)(gbase) + (voff)[_i]), (PG8_LAS unsigned*)(lds + (bufoff) + ldsw + _i * 8192), 16, 0, 0); } while (0)
; #define PG8_LDA(dst, b, h) do { _Pragma("unroll") for (int m = 0; m < 4; ++m) _Pragma("unroll") for (int k = 0; k < 2; ++k) dst[m][k] = *(const PG8_LAS bf16x8*)(lds + PG8_SA(b, h) + aoff + m * 2048 + k * 1024); } while (0)
; #define PG8_LDB(dst, b, h) do { _Pragma("unroll") for (int n = 0; n < 2; ++n) _Pragma("unroll") for (int k = 0; k < 2; ++k) dst[n][k] = *(const PG8_LAS bf16x8*)(lds + PG8_SB(b, h) + boff + n * 2048 + k * 1024); } while (0)
; #define PG8_MMA(ai, bj, At, Bt) do { __builtin_amdgcn_s_setprio(1); _Pragma("unroll") for (int m = 0; m < 4; ++m) _Pragma("unroll") for (int n = 0; n < 2; ++n) _Pragma("unroll") for (int k = 0; k < 2; ++k) \
;         acc[ai][bj][m][n] = __builtin_amdgcn_mfma_f32_16x16x32_bf16(Bt[n][k], At[m][k], acc[ai][bj][m][n], 0, 0, 0); __builtin_amdgcn_s_setprio(0); } while (0)
; #define PG8_WAIT_V(n) asm volatile("s_waitcnt vmcnt(" #n ")" ::: "memory")
; #define PG8_WAIT_L(n) asm volatile("s_waitcnt lgkmcnt(" #n ")" ::: "memory")
; #define PG8_BAR __builtin_amdgcn_s_barrier()
; #define PG8_SCHED __builtin_amdgcn_sched_barrier(0)
; template <class Epi, class Sched, bool ALIGN_EPI = false, bool SP2 = false>
; __device__ __forceinline__ void gemm_phase(PG8_LAS unsigned char* lds, const Gemm g, const Sched& S, const Epi& E) {
;     ...
;             PG8_WAIT_V(8); PG8_WAIT_L(0); PG8_BAR; PG8_MMA(1, 0, At, B0); PG8_MMA(1, 1, At, B1); PG8_BAR; PG8_SCHED;
;             PG8_LDB(B0, 1, 0); PG8_LDB(B1, 1, 1); PG8_SCHED; PG8_LDA(At, 1, 0); PG8_STAGE(PG8_SA(0, 1), a2 + hstep, voffA);
;             PG8_WAIT_V(8); PG8_WAIT_L(0); PG8_BAR; PG8_MMA(0, 0, At, B0); PG8_MMA(0, 1, At, B1); PG8_BAR; PG8_SCHED;
	s_setprio 1
	s_waitcnt lgkmcnt(0)
	v_mfma_f32_16x16x32_bf16 v[60:63], v[114:117], v[162:165], v[60:63]
	v_mfma_f32_16x16x32_bf16 v[56:59], v[126:129], v[162:165], v[56:59]
	v_mfma_f32_16x16x32_bf16 v[44:47], v[114:117], v[170:173], v[44:47]
	v_mfma_f32_16x16x32_bf16 v[40:43], v[126:129], v[170:173], v[40:43]
	v_mfma_f32_16x16x32_bf16 v[28:31], v[114:117], v[178:181], v[28:31]
	v_mfma_f32_16x16x32_bf16 v[24:27], v[126:129], v[178:181], v[24:27]
	v_mfma_f32_16x16x32_bf16 v[12:15], v[114:117], v[186:189], v[12:15]
	v_mfma_f32_16x16x32_bf16 v[8:11], v[126:129], v[186:189], v[8:11]
	v_mfma_f32_16x16x32_bf16 v[60:63], v[118:121], v[166:169], v[60:63]
	v_mfma_f32_16x16x32_bf16 v[56:59], v[130:133], v[166:169], v[56:59]
	v_mfma_f32_16x16x32_bf16 v[44:47], v[118:121], v[174:177], v[44:47]
	v_mfma_f32_16x16x32_bf16 v[40:43], v[130:133], v[174:177], v[40:43]
	v_mfma_f32_16x16x32_bf16 v[28:31], v[118:121], v[182:185], v[28:31]
	v_mfma_f32_16x16x32_bf16 v[24:27], v[130:133], v[182:185], v[24:27]
	v_mfma_f32_16x16x32_bf16 v[12:15], v[118:121], v[190:193], v[12:15]
	v_mfma_f32_16x16x32_bf16 v[8:11], v[130:133], v[190:193], v[8:11]
	v_mfma_f32_16x16x32_bf16 v[52:55], v[138:141], v[162:165], v[52:55]
	v_mfma_f32_16x16x32_bf16 v[48:51], v[146:149], v[162:165], v[48:51]
	v_mfma_f32_16x16x32_bf16 v[36:39], v[138:141], v[170:173], v[36:39]
	v_mfma_f32_16x16x32_bf16 v[32:35], v[146:149], v[170:173], v[32:35]
	v_mfma_f32_16x16x32_bf16 v[20:23], v[138:141], v[178:181], v[20:23]
	v_mfma_f32_16x16x32_bf16 v[16:19], v[146:149], v[178:181], v[16:19]
	v_mfma_f32_16x16x32_bf16 v[4:7], v[138:141], v[186:189], v[4:7]
	v_mfma_f32_16x16x32_bf16 v[0:3], v[146:149], v[186:189], v[0:3]
	v_mfma_f32_16x16x32_bf16 v[52:55], v[142:145], v[166:169], v[52:55]
	v_mfma_f32_16x16x32_bf16 v[48:51], v[158:161], v[166:169], v[48:51]
	v_mfma_f32_16x16x32_bf16 v[36:39], v[142:145], v[174:177], v[36:39]
	v_mfma_f32_16x16x32_bf16 v[32:35], v[158:161], v[174:177], v[32:35]
	v_mfma_f32_16x16x32_bf16 v[20:23], v[142:145], v[182:185], v[20:23]
	v_mfma_f32_16x16x32_bf16 v[16:19], v[158:161], v[182:185], v[16:19]
	v_mfma_f32_16x16x32_bf16 v[4:7], v[142:145], v[190:193], v[4:7]
	v_mfma_f32_16x16x32_bf16 v[0:3], v[158:161], v[190:193], v[0:3]
	s_setprio 0
	s_barrier
	s_add_i32 s84, 0, 0x18000
	s_add_i32 s85, 0, 0x1c000
	v_add_u32_e32 v130, s84, v247
	v_add_u32_e32 v158, s85, v247
	ds_read_b128 v[114:117], v130
	ds_read_b128 v[118:121], v130 offset:1024
	ds_read_b128 v[126:129], v130 offset:2048
	ds_read_b128 v[130:133], v130 offset:3072
	ds_read_b128 v[138:141], v158
	ds_read_b128 v[142:145], v158 offset:1024
	ds_read_b128 v[146:149], v158 offset:2048
	ds_read_b128 v[158:161], v158 offset:3072
	s_add_u32 s12, s62, 0x200000
	s_addc_u32 s13, s63, 0
	s_mov_b32 m0, s66
	v_lshl_add_u64 v[222:223], s[12:13], 0, v[202:203]
	ds_read_b128 v[162:165], v249 offset:32768
	ds_read_b128 v[166:169], v249 offset:33792
	ds_read_b128 v[170:173], v249 offset:34816
	ds_read_b128 v[174:177], v249 offset:35840
	ds_read_b128 v[178:181], v249 offset:36864
	ds_read_b128 v[182:185], v249 offset:37888
	ds_read_b128 v[186:189], v249 offset:38912
	ds_read_b128 v[190:193], v249 offset:39936
	global_load_lds_dwordx4 v[222:223], off
	v_lshl_add_u64 v[222:223], s[12:13], 0, v[206:207]
	s_mov_b32 m0, s67
	s_nop 0
	global_load_lds_dwordx4 v[222:223], off
	s_waitcnt vmcnt(8)
	s_waitcnt lgkmcnt(0)
	s_barrier
	s_setprio 1
	s_waitcnt lgkmcnt(0)
	v_mfma_f32_16x16x32_bf16 v[154:157], v[114:117], v[162:165], v[154:157]
	v_mfma_f32_16x16x32_bf16 v[150:153], v[126:129], v[162:165], v[150:153]
	v_mfma_f32_16x16x32_bf16 v[110:113], v[114:117], v[170:173], v[110:113]
	v_mfma_f32_16x16x32_bf16 v[106:109], v[126:129], v[170:173], v[106:109]
	v_mfma_f32_16x16x32_bf16 v[92:95], v[114:117], v[178:181], v[92:95]
	v_mfma_f32_16x16x32_bf16 v[88:91], v[126:129], v[178:181], v[88:91]
	v_mfma_f32_16x16x32_bf16 v[76:79], v[114:117], v[186:189], v[76:79]
	v_mfma_f32_16x16x32_bf16 v[72:75], v[126:129], v[186:189], v[72:75]
	v_mfma_f32_16x16x32_bf16 v[154:157], v[118:121], v[166:169], v[154:157]
	v_mfma_f32_16x16x32_bf16 v[150:153], v[130:133], v[166:169], v[150:153]
	v_mfma_f32_16x16x32_bf16 v[110:113], v[118:121], v[174:177], v[110:113]
	v_mfma_f32_16x16x32_bf16 v[106:109], v[130:133], v[174:177], v[106:109]
	v_mfma_f32_16x16x32_bf16 v[92:95], v[118:121], v[182:185], v[92:95]
	v_mfma_f32_16x16x32_bf16 v[88:91], v[130:133], v[182:185], v[88:91]
	v_mfma_f32_16x16x32_bf16 v[76:79], v[118:121], v[190:193], v[76:79]
	v_mfma_f32_16x16x32_bf16 v[72:75], v[130:133], v[190:193], v[72:75]
	v_mfma_f32_16x16x32_bf16 v[134:137], v[138:141], v[162:165], v[134:137]
	v_mfma_f32_16x16x32_bf16 v[122:125], v[146:149], v[162:165], v[122:125]
	v_mfma_f32_16x16x32_bf16 v[102:105], v[138:141], v[170:173], v[102:105]
	v_mfma_f32_16x16x32_bf16 v[98:101], v[146:149], v[170:173], v[98:101]
	v_mfma_f32_16x16x32_bf16 v[84:87], v[138:141], v[178:181], v[84:87]
	v_mfma_f32_16x16x32_bf16 v[80:83], v[146:149], v[178:181], v[80:83]
	v_mfma_f32_16x16x32_bf16 v[68:71], v[138:141], v[186:189], v[68:71]
	v_mfma_f32_16x16x32_bf16 v[64:67], v[146:149], v[186:189], v[64:67]
	v_mfma_f32_16x16x32_bf16 v[134:137], v[142:145], v[166:169], v[134:137]
	v_mfma_f32_16x16x32_bf16 v[122:125], v[158:161], v[166:169], v[122:125]
	v_mfma_f32_16x16x32_bf16 v[102:105], v[142:145], v[174:177], v[102:105]
	v_mfma_f32_16x16x32_bf16 v[98:101], v[158:161], v[174:177], v[98:101]
	v_mfma_f32_16x16x32_bf16 v[84:87], v[142:145], v[182:185], v[84:87]
	v_mfma_f32_16x16x32_bf16 v[80:83], v[158:161], v[182:185], v[80:83]
	v_mfma_f32_16x16x32_bf16 v[68:71], v[142:145], v[190:193], v[68:71]
	v_mfma_f32_16x16x32_bf16 v[64:67], v[158:161], v[190:193], v[64:67]
	s_setprio 0
	s_barrier
; #define PG8_STAGE(bufoff, gbase, voff) do { _Pragma("unroll") for (int _i = 0; _i < 2; ++_i) \
;         __builtin_amdgcn_global_load_lds((const unsigned*)((const char*)(gbase) + (voff)[_i]), (PG8_LAS unsigned*)(lds + (bufoff) + ldsw + _i * 8192), 16, 0, 0); } while (0)
; #define PG8_LDA(dst, b, h) do { _Pragma("unroll") for (int m = 0; m < 4; ++m) _Pragma("unroll") for (int k = 0; k < 2; ++k) dst[m][k] = *(const PG8_LAS bf16x8*)(lds + PG8_SA(b, h) + aoff + m * 2048 + k * 1024); } while (0)
; #define PG8_MMA(ai, bj, At, Bt) do { __builtin_amdgcn_s_setprio(1); _Pragma("unroll") for (int m = 0; m < 4; ++m) _Pragma("unroll") for (int n = 0; n < 2; ++n) _Pragma("unroll") for (int k = 0; k < 2; ++k) \
;         acc[ai][bj][m][n] = __builtin_amdgcn_mfma_f32_16x16x32_bf16(Bt[n][k], At[m][k], acc[ai][bj][m][n], 0, 0, 0); __builtin_amdgcn_s_setprio(0); } while (0)
; #define PG8_WAIT_V(n) asm volatile("s_waitcnt vmcnt(" #n ")" ::: "memory")
; #define PG8_WAIT_L(n) asm volatile("s_waitcnt lgkmcnt(" #n ")" ::: "memory")
; #define PG8_BAR __builtin_amdgcn_s_barrier()
; #define PG8_SCHED __builtin_amdgcn_sched_barrier(0)
; template <class Epi, class Sched, bool ALIGN_EPI = false, bool SP2 = false>
; __device__ __forceinline__ void gemm_phase(PG8_LAS unsigned char* lds, const Gemm g, const Sched& S, const Epi& E) {
;     ...
;         for (int t = 0; t < nt; t += 2) {
;             const bool last = (t == nt - 2);
;     ...
;             PG8_LDA(At, 1, 1); PG8_STAGE(PG8_SB(1, 0), b3, voffB); PG8_STAGE(PG8_SB(1, 1), b3 + hstep, voffB); PG8_STAGE(PG8_SA(1, 0), a3, voffA);
;             PG8_WAIT_V(8); PG8_WAIT_L(0); PG8_BAR; PG8_MMA(1, 0, At, B0); PG8_MMA(1, 1, At, B1); PG8_BAR; PG8_SCHED;
	s_add_i32 s12, s84, s11
	v_lshl_add_u64 v[214:215], v[214:215], 0, s[36:37]
	s_mov_b32 m0, s12
	ds_read_b128 v[162:165], v249 offset:49152
	ds_read_b128 v[166:169], v249 offset:50176
	ds_read_b128 v[170:173], v249 offset:51200
	ds_read_b128 v[174:177], v249 offset:52224
	ds_read_b128 v[178:181], v249 offset:53248
	ds_read_b128 v[182:185], v249 offset:54272
	ds_read_b128 v[186:189], v249 offset:55296
	ds_read_b128 v[190:193], v249 offset:56320
	global_load_lds_dwordx4 v[214:215], off
	s_add_i32 m0, s12, 0x2000
	s_add_u32 s12, s60, 0x200080
	v_lshl_add_u64 v[214:215], v[216:217], 0, s[36:37]
	s_addc_u32 s13, s61, 0
	s_add_i32 s60, s85, s11
	global_load_lds_dwordx4 v[214:215], off
	v_lshl_add_u64 v[214:215], s[12:13], 0, v[204:205]
	s_mov_b32 m0, s60
	s_nop 0
	global_load_lds_dwordx4 v[214:215], off
	v_lshl_add_u64 v[214:215], s[12:13], 0, v[208:209]
	s_add_i32 m0, s60, 0x2000
	s_nop 0
	global_load_lds_dwordx4 v[214:215], off
	v_lshl_add_u64 v[214:215], v[218:219], 0, s[36:37]
	s_mov_b32 m0, s69
	s_nop 0
	global_load_lds_dwordx4 v[214:215], off
	v_lshl_add_u64 v[214:215], v[220:221], 0, s[36:37]
	s_mov_b32 m0, s70
	s_nop 0
	global_load_lds_dwordx4 v[214:215], off
	s_waitcnt vmcnt(8)
	s_waitcnt lgkmcnt(0)
	s_barrier
	s_setprio 1
	s_waitcnt lgkmcnt(0)
	v_mfma_f32_16x16x32_bf16 v[60:63], v[114:117], v[162:165], v[60:63]
	v_mfma_f32_16x16x32_bf16 v[56:59], v[126:129], v[162:165], v[56:59]
	v_mfma_f32_16x16x32_bf16 v[44:47], v[114:117], v[170:173], v[44:47]
	v_mfma_f32_16x16x32_bf16 v[40:43], v[126:129], v[170:173], v[40:43]
	v_mfma_f32_16x16x32_bf16 v[28:31], v[114:117], v[178:181], v[28:31]
	v_mfma_f32_16x16x32_bf16 v[24:27], v[126:129], v[178:181], v[24:27]
	v_mfma_f32_16x16x32_bf16 v[12:15], v[114:117], v[186:189], v[12:15]
	v_mfma_f32_16x16x32_bf16 v[8:11], v[126:129], v[186:189], v[8:11]
	v_mfma_f32_16x16x32_bf16 v[60:63], v[118:121], v[166:169], v[60:63]
	v_mfma_f32_16x16x32_bf16 v[56:59], v[130:133], v[166:169], v[56:59]
	v_mfma_f32_16x16x32_bf16 v[44:47], v[118:121], v[174:177], v[44:47]
	v_mfma_f32_16x16x32_bf16 v[40:43], v[130:133], v[174:177], v[40:43]
	v_mfma_f32_16x16x32_bf16 v[28:31], v[118:121], v[182:185], v[28:31]
	v_mfma_f32_16x16x32_bf16 v[24:27], v[130:133], v[182:185], v[24:27]
	v_mfma_f32_16x16x32_bf16 v[12:15], v[118:121], v[190:193], v[12:15]
	v_mfma_f32_16x16x32_bf16 v[8:11], v[130:133], v[190:193], v[8:11]
	v_mfma_f32_16x16x32_bf16 v[52:55], v[138:141], v[162:165], v[52:55]
	v_mfma_f32_16x16x32_bf16 v[48:51], v[146:149], v[162:165], v[48:51]
	v_mfma_f32_16x16x32_bf16 v[36:39], v[138:141], v[170:173], v[36:39]
	v_mfma_f32_16x16x32_bf16 v[32:35], v[146:149], v[170:173], v[32:35]
	v_mfma_f32_16x16x32_bf16 v[20:23], v[138:141], v[178:181], v[20:23]
	v_mfma_f32_16x16x32_bf16 v[16:19], v[146:149], v[178:181], v[16:19]
	v_mfma_f32_16x16x32_bf16 v[4:7], v[138:141], v[186:189], v[4:7]
	v_mfma_f32_16x16x32_bf16 v[0:3], v[146:149], v[186:189], v[0:3]
	v_mfma_f32_16x16x32_bf16 v[52:55], v[142:145], v[166:169], v[52:55]
	v_mfma_f32_16x16x32_bf16 v[48:51], v[158:161], v[166:169], v[48:51]
	v_mfma_f32_16x16x32_bf16 v[36:39], v[142:145], v[174:177], v[36:39]
	v_mfma_f32_16x16x32_bf16 v[32:35], v[158:161], v[174:177], v[32:35]
	v_mfma_f32_16x16x32_bf16 v[20:23], v[142:145], v[182:185], v[20:23]
	v_mfma_f32_16x16x32_bf16 v[16:19], v[158:161], v[182:185], v[16:19]
	v_mfma_f32_16x16x32_bf16 v[4:7], v[142:145], v[190:193], v[4:7]
	v_mfma_f32_16x16x32_bf16 v[0:3], v[158:161], v[190:193], v[0:3]
	s_setprio 0
	s_barrier
	s_add_i32 s73, s73, 2
	s_add_u32 s49, s49, 0x100
	s_addc_u32 s55, s55, 0
	s_add_u32 s58, s58, 0x100
	s_addc_u32 s59, s59, 0
	s_cmpk_gt_u32 s73, 0x7d
	s_cbranch_scc0 .LBB0_1144
	s_and_b64 vcc, exec, s[14:15]
	s_cbranch_vccz .LBB0_1147
	s_barrier
